# natten: batched V staging + 8-deep prefetched K ring, unmasked bias reads; flash D: fragments prefetched + MFMA/VALU interleave; flash A/C/D: cross-half max exchange moved to the rare rescale path
# speedup vs baseline: 1.0093x; 1.0093x over previous
; #define MFMA32(a, b, c) __builtin_amdgcn_mfma_f32_32x32x16_bf16((a), (b), (c), 0, 0, 0)
; template <int DQK, int NSUB, int MODE>
; __device__ __forceinline__ void flash_unit(LAS char* L, const bf16_t* Qp, int qpitch, const bf16_t* Kp, int kpitch, const bf16_t* Vp, int vpitch,
;                                            bf16_t* Op, int opitch, float lam, float oscale, const float* subln) {
;     ...
;         for (int s = 0; s < NSUB; ++s) {
;             f32x16 p0, p1;
; #pragma unroll
;             for (int d0 = 0; d0 < ND0; ++d0) { const bf16x8 k0 = *(const bf16x8*)(Kb + r32 * KPB + (s * DQK + 16 * d0 + 8 * hi) * 2); const bf16x8 k1 = *(const bf16x8*)(Kb + (32 + r32) * KPB + (s * DQK + 16 * d0 + 8 * hi) * 2);
;                 if (d0 == 0) { p0 = MFMA32(k0, qf[s][d0], negm[s]); p1 = MFMA32(k1, qf[s][d0], negm[s]); }
;                 else { p0 = MFMA32(k0, qf[s][d0], p0); p1 = MFMA32(k1, qf[s][d0], p1); } }
; #pragma unroll
;             for (int hf = 0; hf < 2; ++hf) {
;                 f32x16& ph = hf ? p1 : p0;
;                 float mx = fmaxf(ph[0], ph[1]);
; #pragma unroll
;                 for (int r = 2; r < 16; ++r) mx = fmaxf(mx, ph[r]);
;                 mx = fmaxf(mx, __shfl_xor(mx, 32));
;                 const bool first = (t == 0) && (hf == 0);
;                 if (first || __any(mx > 8.0f)) {
;                     const float dl = first ? mx : fmaxf(mx, 0.f); mref[s] += dl;
; #pragma unroll
;                     for (int r = 0; r < 16; ++r) { ph[r] -= dl; negm[s][r] = -mref[s]; }
;                     if (hf == 0) {
; #pragma unroll
;                         for (int r = 0; r < 16; ++r) p1[r] -= dl;
;                     }
;                     if (!first) { const float alpha = __builtin_amdgcn_exp2f(-dl); lrow[s] *= alpha;
; #pragma unroll
;                         for (int r = 0; r < 16; ++r) { o[s][0][r] *= alpha; o[s][1][r] *= alpha; } }
;                 }
; #pragma unroll
;                 for (int r = 0; r < 16; ++r) ph[r] = __builtin_amdgcn_exp2f(ph[r]);
;                 { typedef float f32x2_ __attribute__((ext_vector_type(2))); f32x2_ r2 = {ph[0], ph[1]};
; #pragma unroll
;                   for (int r = 2; r < 16; r += 2) r2 += (f32x2_){ph[r], ph[r + 1]};
;                   lrow[s] += r2[0] + r2[1]; }
;                 bf16x8 pf[2];
; #pragma unroll
;                 for (int k2 = 0; k2 < 2; ++k2) { u32x4 w;
; #pragma unroll
.LBB0_579:
	s_and_b32 s8, s22, 1
	s_mul_i32 s9, s8, 0x2400
	v_add_u32_e32 v195, s9, v192
	ds_read_b128 v[96:99], v195
	ds_read_b128 v[100:103], v195 offset:32
	ds_read_b128 v[170:173], v195 offset:4608
	ds_read_b128 v[174:177], v195 offset:4640
	s_waitcnt lgkmcnt(0)
	v_mfma_f32_32x32x16_bf16 v[112:127], v[96:99], v[128:131], v[32:47]
	v_mfma_f32_32x32x16_bf16 v[112:127], v[100:103], v[132:135], v[112:127]
	v_mov_b64_e32 v[110:111], v[46:47]
	v_mov_b64_e32 v[108:109], v[44:45]
	v_mov_b64_e32 v[106:107], v[42:43]
	v_mov_b64_e32 v[104:105], v[40:41]
	v_mov_b64_e32 v[102:103], v[38:39]
	v_mov_b64_e32 v[100:101], v[36:37]
	v_mov_b64_e32 v[98:99], v[34:35]
	v_mov_b64_e32 v[96:97], v[32:33]
	s_nop 3
	v_max_f32_e32 v158, v113, v113
	v_max_f32_e32 v169, v112, v112
	v_mfma_f32_32x32x16_bf16 v[96:111], v[170:173], v[128:131], v[96:111]
	v_max_f32_e32 v158, v169, v158
	v_max3_f32 v158, v158, v114, v115
	v_max3_f32 v158, v158, v116, v117
	v_max3_f32 v158, v158, v118, v119
	v_max3_f32 v158, v158, v120, v121
	v_max3_f32 v158, v158, v122, v123
	v_max3_f32 v158, v158, v124, v125
	v_max3_f32 v158, v158, v126, v127
	v_mfma_f32_32x32x16_bf16 v[96:111], v[174:177], v[132:135], v[96:111]
	v_cmp_lt_f32_e32 vcc, s61, v158
	s_cbranch_vccz .LBB0_581
	ds_bpermute_b32 v169, v184, v158
	s_waitcnt lgkmcnt(0)
	v_max_f32_e32 v169, v169, v169
	v_max_f32_e32 v158, v158, v169
	v_max_f32_e32 v32, v158, v158
	v_max_f32_e32 v34, 0, v32
	v_exp_f32_e64 v36, -v34
	v_add_f32_e32 v159, v159, v34
	v_xor_b32_e32 v32, 0x80000000, v159
	v_pk_add_f32 v[112:113], v[112:113], v[34:35] op_sel_hi:[1,0] neg_lo:[0,1] neg_hi:[0,1]
	v_pk_add_f32 v[114:115], v[114:115], v[34:35] op_sel_hi:[1,0] neg_lo:[0,1] neg_hi:[0,1]
	v_pk_add_f32 v[116:117], v[116:117], v[34:35] op_sel_hi:[1,0] neg_lo:[0,1] neg_hi:[0,1]
	v_pk_add_f32 v[118:119], v[118:119], v[34:35] op_sel_hi:[1,0] neg_lo:[0,1] neg_hi:[0,1]
	v_pk_add_f32 v[120:121], v[120:121], v[34:35] op_sel_hi:[1,0] neg_lo:[0,1] neg_hi:[0,1]
	v_pk_add_f32 v[122:123], v[122:123], v[34:35] op_sel_hi:[1,0] neg_lo:[0,1] neg_hi:[0,1]
	v_pk_add_f32 v[124:125], v[124:125], v[34:35] op_sel_hi:[1,0] neg_lo:[0,1] neg_hi:[0,1]
	v_pk_add_f32 v[126:127], v[126:127], v[34:35] op_sel_hi:[1,0] neg_lo:[0,1] neg_hi:[0,1]
	v_sub_f32_e32 v111, v111, v34
	v_sub_f32_e32 v110, v110, v34
	v_sub_f32_e32 v109, v109, v34
	v_sub_f32_e32 v108, v108, v34
	v_sub_f32_e32 v107, v107, v34
	v_sub_f32_e32 v106, v106, v34
	v_sub_f32_e32 v105, v105, v34
	v_sub_f32_e32 v104, v104, v34
	v_sub_f32_e32 v103, v103, v34
	v_sub_f32_e32 v102, v102, v34
	v_sub_f32_e32 v101, v101, v34
	v_sub_f32_e32 v100, v100, v34
	v_sub_f32_e32 v99, v99, v34
	v_sub_f32_e32 v98, v98, v34
	v_sub_f32_e32 v97, v97, v34
	v_sub_f32_e32 v96, v96, v34
	v_pk_mul_f32 v[14:15], v[14:15], v[36:37] op_sel_hi:[1,0]
	v_pk_mul_f32 v[12:13], v[12:13], v[36:37] op_sel_hi:[1,0]
	v_pk_mul_f32 v[10:11], v[10:11], v[36:37] op_sel_hi:[1,0]
	v_pk_mul_f32 v[8:9], v[8:9], v[36:37] op_sel_hi:[1,0]
	v_pk_mul_f32 v[6:7], v[6:7], v[36:37] op_sel_hi:[1,0]
	v_pk_mul_f32 v[4:5], v[4:5], v[36:37] op_sel_hi:[1,0]
	v_pk_mul_f32 v[2:3], v[2:3], v[36:37] op_sel_hi:[1,0]
	v_pk_mul_f32 v[0:1], v[0:1], v[36:37] op_sel_hi:[1,0]
	v_pk_mul_f32 v[30:31], v[30:31], v[36:37] op_sel_hi:[1,0]
	v_pk_mul_f32 v[28:29], v[28:29], v[36:37] op_sel_hi:[1,0]
	v_pk_mul_f32 v[26:27], v[26:27], v[36:37] op_sel_hi:[1,0]
	v_pk_mul_f32 v[24:25], v[24:25], v[36:37] op_sel_hi:[1,0]
	v_pk_mul_f32 v[22:23], v[22:23], v[36:37] op_sel_hi:[1,0]
	v_pk_mul_f32 v[20:21], v[20:21], v[36:37] op_sel_hi:[1,0]
	v_pk_mul_f32 v[18:19], v[18:19], v[36:37] op_sel_hi:[1,0]
	v_pk_mul_f32 v[16:17], v[16:17], v[36:37] op_sel_hi:[1,0]
	v_mul_f32_e32 v168, v168, v36
	v_mov_b32_e32 v33, v32
	v_mov_b32_e32 v34, v32
	v_mov_b32_e32 v35, v32
	v_mov_b32_e32 v36, v32
	v_mov_b32_e32 v37, v32
	v_mov_b32_e32 v38, v32
	v_mov_b32_e32 v39, v32
	v_mov_b32_e32 v40, v32
	v_mov_b32_e32 v41, v32
	v_mov_b32_e32 v42, v32
	v_mov_b32_e32 v43, v32
	v_mov_b32_e32 v44, v32
	v_mov_b32_e32 v45, v32
	v_mov_b32_e32 v46, v32
	v_mov_b32_e32 v47, v32
.LBB0_581:
	v_exp_f32_e32 v112, v112
	v_exp_f32_e32 v113, v113
	v_exp_f32_e32 v114, v114
	v_exp_f32_e32 v115, v115
	v_exp_f32_e32 v116, v116
	v_exp_f32_e32 v117, v117
	v_exp_f32_e32 v118, v118
	v_exp_f32_e32 v119, v119
	v_exp_f32_e32 v120, v120
	v_exp_f32_e32 v121, v121
	v_exp_f32_e32 v122, v122
	v_exp_f32_e32 v123, v123
	v_pk_add_f32 v[170:171], v[112:113], v[114:115]
	v_add_u32_e32 v158, s9, v191
	v_pk_add_f32 v[170:171], v[116:117], v[170:171]
	v_cvt_pk_bf16_f32 v112, v112, v113
	v_pk_add_f32 v[170:171], v[118:119], v[170:171]
	v_cvt_pk_bf16_f32 v113, v114, v115
	v_pk_add_f32 v[170:171], v[120:121], v[170:171]
	v_cvt_pk_bf16_f32 v114, v116, v117
	v_pk_add_f32 v[170:171], v[122:123], v[170:171]
	v_cvt_pk_bf16_f32 v116, v120, v121
	v_cvt_pk_bf16_f32 v117, v122, v123
	ds_read_b64_tr_b16 v[120:121], v158 offset:18432
	ds_read_b64_tr_b16 v[122:123], v158 offset:19584
	v_cvt_pk_bf16_f32 v115, v118, v119
	v_exp_f32_e32 v124, v124
	v_exp_f32_e32 v125, v125
	s_waitcnt lgkmcnt(0)
	v_mfma_f32_32x32x16_bf16 v[0:15], v[120:123], v[112:115], v[0:15]
	v_exp_f32_e32 v126, v126
	v_exp_f32_e32 v127, v127
	ds_read_b64_tr_b16 v[120:121], v158 offset:20736
	ds_read_b64_tr_b16 v[122:123], v158 offset:21888
	v_cvt_pk_bf16_f32 v118, v124, v125
	v_pk_add_f32 v[170:171], v[124:125], v[170:171]
	v_cvt_pk_bf16_f32 v119, v126, v127
	v_pk_add_f32 v[170:171], v[126:127], v[170:171]
	s_waitcnt lgkmcnt(0)
	v_mfma_f32_32x32x16_bf16 v[0:15], v[120:123], v[116:119], v[0:15]
	ds_read_b64_tr_b16 v[120:121], v158 offset:18496
	ds_read_b64_tr_b16 v[122:123], v158 offset:19648
	v_add_f32_e32 v169, v170, v171
	v_add_f32_e32 v194, v168, v169
	s_waitcnt lgkmcnt(0)
	v_mfma_f32_32x32x16_bf16 v[16:31], v[120:123], v[112:115], v[16:31]
	ds_read_b64_tr_b16 v[112:113], v158 offset:20800
	ds_read_b64_tr_b16 v[114:115], v158 offset:21952
	s_waitcnt lgkmcnt(0)
	v_mfma_f32_32x32x16_bf16 v[16:31], v[112:115], v[116:119], v[16:31]
	v_max_f32_e32 v112, v97, v97
	v_max_f32_e32 v113, v96, v96
	v_max_f32_e32 v112, v113, v112
	v_max3_f32 v112, v112, v98, v99
	v_max3_f32 v112, v112, v100, v101
	v_max3_f32 v112, v112, v102, v103
	v_max3_f32 v112, v112, v104, v105
	v_max3_f32 v112, v112, v106, v107
	v_max3_f32 v112, v112, v108, v109
	v_max3_f32 v112, v112, v110, v111
	v_cmp_lt_f32_e32 vcc, s61, v112
	s_cbranch_vccz .LBB0_583
; template <int DQK, int NSUB, int MODE>
; __device__ __forceinline__ void flash_unit(LAS char* L, const bf16_t* Qp, int qpitch, const bf16_t* Kp, int kpitch, const bf16_t* Vp, int vpitch,
;                                            bf16_t* Op, int opitch, float lam, float oscale, const float* subln) {
;     ...
;             for (int d0 = 0; d0 < ND0; ++d0) { const bf16x8 k0 = *(const bf16x8*)(Kb + r32 * KPB + (s * DQK + 16 * d0 + 8 * hi) * 2); const bf16x8 k1 = *(const bf16x8*)(Kb + (32 + r32) * KPB + (s * DQK + 16 * d0 + 8 * hi) * 2);
;                 if (d0 == 0) { p0 = MFMA32(k0, qf[s][d0], negm[s]); p1 = MFMA32(k1, qf[s][d0], negm[s]); }
;                 else { p0 = MFMA32(k0, qf[s][d0], p0); p1 = MFMA32(k1, qf[s][d0], p1); } }
; #pragma unroll
;             for (int hf = 0; hf < 2; ++hf) {
;                 f32x16& ph = hf ? p1 : p0;
;                 float mx = fmaxf(ph[0], ph[1]);
; #pragma unroll
;                 for (int r = 2; r < 16; ++r) mx = fmaxf(mx, ph[r]);
;                 mx = fmaxf(mx, __shfl_xor(mx, 32));
;                 const bool first = (t == 0) && (hf == 0);
;                 if (first || __any(mx > 8.0f)) {
;                     const float dl = first ? mx : fmaxf(mx, 0.f); mref[s] += dl;
; #pragma unroll
;                     for (int r = 0; r < 16; ++r) { ph[r] -= dl; negm[s][r] = -mref[s]; }
;                     if (hf == 0) {
; #pragma unroll
;                         for (int r = 0; r < 16; ++r) p1[r] -= dl;
;                     }
;                     if (!first) { const float alpha = __builtin_amdgcn_exp2f(-dl); lrow[s] *= alpha;
; #pragma unroll
;                         for (int r = 0; r < 16; ++r) { o[s][0][r] *= alpha; o[s][1][r] *= alpha; } }
;                 }
; #pragma unroll
;                 for (int r = 0; r < 16; ++r) ph[r] = __builtin_amdgcn_exp2f(ph[r]);
;                 { typedef float f32x2_ __attribute__((ext_vector_type(2))); f32x2_ r2 = {ph[0], ph[1]};
; #pragma unroll
;                   for (int r = 2; r < 16; r += 2) r2 += (f32x2_){ph[r], ph[r + 1]};
;                   lrow[s] += r2[0] + r2[1]; }
;                 bf16x8 pf[2];
; #pragma unroll
;                 for (int k2 = 0; k2 < 2; ++k2) { u32x4 w;
; #pragma unroll
;                     for (int e = 0; e < 4; ++e) w[e] = cvt_pk_bf16(ph[8 * k2 + 2 * e], ph[8 * k2 + 2 * e + 1]);
;                     pf[k2] = __builtin_bit_cast(bf16x8, w); }
	ds_bpermute_b32 v113, v184, v112
	s_waitcnt lgkmcnt(0)
	v_max_f32_e32 v113, v113, v113
	v_max_f32_e32 v112, v112, v113
	v_max_f32_e32 v32, v112, v112
	v_max_f32_e32 v34, 0, v32
	v_exp_f32_e64 v36, -v34
	v_add_f32_e32 v159, v159, v34
	v_xor_b32_e32 v32, 0x80000000, v159
	v_pk_add_f32 v[96:97], v[96:97], v[34:35] op_sel_hi:[1,0] neg_lo:[0,1] neg_hi:[0,1]
	v_pk_add_f32 v[98:99], v[98:99], v[34:35] op_sel_hi:[1,0] neg_lo:[0,1] neg_hi:[0,1]
	v_pk_add_f32 v[100:101], v[100:101], v[34:35] op_sel_hi:[1,0] neg_lo:[0,1] neg_hi:[0,1]
	v_pk_add_f32 v[102:103], v[102:103], v[34:35] op_sel_hi:[1,0] neg_lo:[0,1] neg_hi:[0,1]
	v_pk_add_f32 v[104:105], v[104:105], v[34:35] op_sel_hi:[1,0] neg_lo:[0,1] neg_hi:[0,1]
	v_pk_add_f32 v[106:107], v[106:107], v[34:35] op_sel_hi:[1,0] neg_lo:[0,1] neg_hi:[0,1]
	v_pk_add_f32 v[108:109], v[108:109], v[34:35] op_sel_hi:[1,0] neg_lo:[0,1] neg_hi:[0,1]
	v_pk_add_f32 v[110:111], v[110:111], v[34:35] op_sel_hi:[1,0] neg_lo:[0,1] neg_hi:[0,1]
	v_pk_mul_f32 v[14:15], v[14:15], v[36:37] op_sel_hi:[1,0]
	v_pk_mul_f32 v[12:13], v[12:13], v[36:37] op_sel_hi:[1,0]
	v_pk_mul_f32 v[10:11], v[10:11], v[36:37] op_sel_hi:[1,0]
	v_pk_mul_f32 v[8:9], v[8:9], v[36:37] op_sel_hi:[1,0]
	v_pk_mul_f32 v[6:7], v[6:7], v[36:37] op_sel_hi:[1,0]
	v_pk_mul_f32 v[4:5], v[4:5], v[36:37] op_sel_hi:[1,0]
	v_pk_mul_f32 v[2:3], v[2:3], v[36:37] op_sel_hi:[1,0]
	v_pk_mul_f32 v[0:1], v[0:1], v[36:37] op_sel_hi:[1,0]
	v_pk_mul_f32 v[30:31], v[30:31], v[36:37] op_sel_hi:[1,0]
	v_pk_mul_f32 v[28:29], v[28:29], v[36:37] op_sel_hi:[1,0]
	v_pk_mul_f32 v[26:27], v[26:27], v[36:37] op_sel_hi:[1,0]
	v_pk_mul_f32 v[24:25], v[24:25], v[36:37] op_sel_hi:[1,0]
	v_pk_mul_f32 v[22:23], v[22:23], v[36:37] op_sel_hi:[1,0]
	v_pk_mul_f32 v[20:21], v[20:21], v[36:37] op_sel_hi:[1,0]
	v_pk_mul_f32 v[18:19], v[18:19], v[36:37] op_sel_hi:[1,0]
	v_pk_mul_f32 v[16:17], v[16:17], v[36:37] op_sel_hi:[1,0]
	v_mul_f32_e32 v194, v194, v36
	v_mov_b32_e32 v33, v32
	v_mov_b32_e32 v34, v32
	v_mov_b32_e32 v35, v32
	v_mov_b32_e32 v36, v32
	v_mov_b32_e32 v37, v32
	v_mov_b32_e32 v38, v32
	v_mov_b32_e32 v39, v32
	v_mov_b32_e32 v40, v32
	v_mov_b32_e32 v41, v32
	v_mov_b32_e32 v42, v32
	v_mov_b32_e32 v43, v32
	v_mov_b32_e32 v44, v32
	v_mov_b32_e32 v45, v32
	v_mov_b32_e32 v46, v32
	v_mov_b32_e32 v47, v32
.LBB0_583:
	v_exp_f32_e32 v168, v96
	v_exp_f32_e32 v169, v97
	v_exp_f32_e32 v170, v98
	v_exp_f32_e32 v171, v99
	v_exp_f32_e32 v172, v100
	v_exp_f32_e32 v173, v101
	v_exp_f32_e32 v174, v102
	v_exp_f32_e32 v175, v103
	v_exp_f32_e32 v176, v104
	v_exp_f32_e32 v177, v105
	v_exp_f32_e32 v178, v106
	v_exp_f32_e32 v179, v107
	ds_read_b64_tr_b16 v[104:105], v158 offset:23040
	ds_read_b64_tr_b16 v[106:107], v158 offset:24192
	v_cvt_pk_bf16_f32 v96, v168, v169
	v_cvt_pk_bf16_f32 v97, v170, v171
	v_cvt_pk_bf16_f32 v98, v172, v173
	v_cvt_pk_bf16_f32 v99, v174, v175
	v_exp_f32_e32 v180, v108
	v_exp_f32_e32 v181, v109
	s_waitcnt lgkmcnt(0)
	v_mfma_f32_32x32x16_bf16 v[0:15], v[104:107], v[96:99], v[0:15]
	v_exp_f32_e32 v182, v110
	v_exp_f32_e32 v183, v111
	ds_read_b64_tr_b16 v[104:105], v158 offset:25344
	ds_read_b64_tr_b16 v[106:107], v158 offset:26496
	v_cvt_pk_bf16_f32 v100, v176, v177
	v_cvt_pk_bf16_f32 v101, v178, v179
	v_cvt_pk_bf16_f32 v102, v180, v181
	v_cvt_pk_bf16_f32 v103, v182, v183
	s_waitcnt lgkmcnt(0)
	s_nop 0
	v_mfma_f32_32x32x16_bf16 v[0:15], v[104:107], v[100:103], v[0:15]
	ds_read_b64_tr_b16 v[104:105], v158 offset:23104
	ds_read_b64_tr_b16 v[106:107], v158 offset:24256
	s_waitcnt lgkmcnt(0)
	v_mfma_f32_32x32x16_bf16 v[16:31], v[104:107], v[96:99], v[16:31]
	ds_read_b64_tr_b16 v[96:97], v158 offset:25408
	ds_read_b64_tr_b16 v[98:99], v158 offset:26560
	s_waitcnt lgkmcnt(0)
	v_mfma_f32_32x32x16_bf16 v[16:31], v[96:99], v[100:103], v[16:31]
	ds_read_b128 v[196:199], v195 offset:4672
	ds_read_b128 v[96:99], v195 offset:64
	ds_read_b128 v[200:203], v195 offset:96
	s_waitcnt lgkmcnt(0)
	v_mfma_f32_32x32x16_bf16 v[112:127], v[96:99], v[136:139], v[80:95]
	v_mov_b64_e32 v[110:111], v[94:95]
	v_mov_b64_e32 v[108:109], v[92:93]
	v_mov_b64_e32 v[106:107], v[90:91]
	v_mov_b64_e32 v[104:105], v[88:89]
	v_mov_b64_e32 v[102:103], v[86:87]
	v_mov_b64_e32 v[100:101], v[84:85]
	v_mov_b64_e32 v[98:99], v[82:83]
	v_mov_b64_e32 v[96:97], v[80:81]
	v_mfma_f32_32x32x16_bf16 v[112:127], v[200:203], v[140:143], v[112:127]
	s_nop 0
	v_mfma_f32_32x32x16_bf16 v[96:111], v[196:199], v[136:139], v[96:111]
	ds_read_b128 v[196:199], v195 offset:4704
	s_nop 8
	v_max_f32_e32 v195, v113, v113
	s_waitcnt lgkmcnt(0)
	v_mfma_f32_32x32x16_bf16 v[96:111], v[196:199], v[140:143], v[96:111]
	v_max_f32_e32 v196, v112, v112
	v_max_f32_e32 v195, v196, v195
	v_max3_f32 v195, v195, v114, v115
	v_max3_f32 v195, v195, v116, v117
	v_max3_f32 v195, v195, v118, v119
	v_max3_f32 v195, v195, v120, v121
	v_max3_f32 v195, v195, v122, v123
	v_max3_f32 v195, v195, v124, v125
	v_max3_f32 v195, v195, v126, v127
	v_cmp_lt_f32_e32 vcc, s61, v195
	s_cbranch_vccz .LBB0_585
; template <int DQK, int NSUB, int MODE>
; __device__ __forceinline__ void flash_unit(LAS char* L, const bf16_t* Qp, int qpitch, const bf16_t* Kp, int kpitch, const bf16_t* Vp, int vpitch,
;                                            bf16_t* Op, int opitch, float lam, float oscale, const float* subln) {
;     ...
;                 if (first || __any(mx > 8.0f)) {
;                     const float dl = first ? mx : fmaxf(mx, 0.f); mref[s] += dl;
; #pragma unroll
;                     for (int r = 0; r < 16; ++r) { ph[r] -= dl; negm[s][r] = -mref[s]; }
;                     if (hf == 0) {
; #pragma unroll
;                         for (int r = 0; r < 16; ++r) p1[r] -= dl;
;                     }
;                     if (!first) { const float alpha = __builtin_amdgcn_exp2f(-dl); lrow[s] *= alpha;
; #pragma unroll
;                         for (int r = 0; r < 16; ++r) { o[s][0][r] *= alpha; o[s][1][r] *= alpha; } }
;                 }
	ds_bpermute_b32 v196, v184, v195
	s_waitcnt lgkmcnt(0)
	v_max_f32_e32 v196, v196, v196
	v_max_f32_e32 v195, v195, v196
	v_max_f32_e32 v80, v195, v195
	v_max_f32_e32 v82, 0, v80
	v_exp_f32_e64 v84, -v82
	v_add_f32_e32 v161, v161, v82
	v_xor_b32_e32 v80, 0x80000000, v161
	v_pk_add_f32 v[112:113], v[112:113], v[82:83] op_sel_hi:[1,0] neg_lo:[0,1] neg_hi:[0,1]
	v_pk_add_f32 v[114:115], v[114:115], v[82:83] op_sel_hi:[1,0] neg_lo:[0,1] neg_hi:[0,1]
	v_pk_add_f32 v[116:117], v[116:117], v[82:83] op_sel_hi:[1,0] neg_lo:[0,1] neg_hi:[0,1]
	v_pk_add_f32 v[118:119], v[118:119], v[82:83] op_sel_hi:[1,0] neg_lo:[0,1] neg_hi:[0,1]
	v_pk_add_f32 v[120:121], v[120:121], v[82:83] op_sel_hi:[1,0] neg_lo:[0,1] neg_hi:[0,1]
	v_pk_add_f32 v[122:123], v[122:123], v[82:83] op_sel_hi:[1,0] neg_lo:[0,1] neg_hi:[0,1]
	v_pk_add_f32 v[124:125], v[124:125], v[82:83] op_sel_hi:[1,0] neg_lo:[0,1] neg_hi:[0,1]
	v_pk_add_f32 v[126:127], v[126:127], v[82:83] op_sel_hi:[1,0] neg_lo:[0,1] neg_hi:[0,1]
	v_sub_f32_e32 v111, v111, v82
	v_sub_f32_e32 v110, v110, v82
	v_sub_f32_e32 v109, v109, v82
	v_sub_f32_e32 v108, v108, v82
	v_sub_f32_e32 v107, v107, v82
	v_sub_f32_e32 v106, v106, v82
	v_sub_f32_e32 v105, v105, v82
	v_sub_f32_e32 v104, v104, v82
	v_sub_f32_e32 v103, v103, v82
	v_sub_f32_e32 v102, v102, v82
	v_sub_f32_e32 v101, v101, v82
	v_sub_f32_e32 v100, v100, v82
	v_sub_f32_e32 v99, v99, v82
	v_sub_f32_e32 v98, v98, v82
	v_sub_f32_e32 v97, v97, v82
	v_sub_f32_e32 v96, v96, v82
	v_pk_mul_f32 v[62:63], v[62:63], v[84:85] op_sel_hi:[1,0]
	v_pk_mul_f32 v[60:61], v[60:61], v[84:85] op_sel_hi:[1,0]
	v_pk_mul_f32 v[58:59], v[58:59], v[84:85] op_sel_hi:[1,0]
	v_pk_mul_f32 v[56:57], v[56:57], v[84:85] op_sel_hi:[1,0]
	v_pk_mul_f32 v[54:55], v[54:55], v[84:85] op_sel_hi:[1,0]
	v_pk_mul_f32 v[52:53], v[52:53], v[84:85] op_sel_hi:[1,0]
	v_pk_mul_f32 v[50:51], v[50:51], v[84:85] op_sel_hi:[1,0]
	v_pk_mul_f32 v[48:49], v[48:49], v[84:85] op_sel_hi:[1,0]
	v_pk_mul_f32 v[78:79], v[78:79], v[84:85] op_sel_hi:[1,0]
	v_pk_mul_f32 v[76:77], v[76:77], v[84:85] op_sel_hi:[1,0]
	v_pk_mul_f32 v[74:75], v[74:75], v[84:85] op_sel_hi:[1,0]
	v_pk_mul_f32 v[72:73], v[72:73], v[84:85] op_sel_hi:[1,0]
	v_pk_mul_f32 v[70:71], v[70:71], v[84:85] op_sel_hi:[1,0]
	v_pk_mul_f32 v[68:69], v[68:69], v[84:85] op_sel_hi:[1,0]
	v_pk_mul_f32 v[66:67], v[66:67], v[84:85] op_sel_hi:[1,0]
	v_pk_mul_f32 v[64:65], v[64:65], v[84:85] op_sel_hi:[1,0]
	v_mul_f32_e32 v160, v160, v84
	v_mov_b32_e32 v81, v80
	v_mov_b32_e32 v82, v80
	v_mov_b32_e32 v83, v80
	v_mov_b32_e32 v84, v80
	v_mov_b32_e32 v85, v80
	v_mov_b32_e32 v86, v80
	v_mov_b32_e32 v87, v80
	v_mov_b32_e32 v88, v80
	v_mov_b32_e32 v89, v80
	v_mov_b32_e32 v90, v80
	v_mov_b32_e32 v91, v80
	v_mov_b32_e32 v92, v80
	v_mov_b32_e32 v93, v80
	v_mov_b32_e32 v94, v80
	v_mov_b32_e32 v95, v80
; __device__ __forceinline__ unsigned cvt_pk_bf16(float lo, float hi) { typedef float f2 __attribute__((ext_vector_type(2))); typedef __bf16 b2 __attribute__((ext_vector_type(2))); f2 v = {lo, hi}; b2 b = __builtin_convertvector(v, b2); return __builtin_bit_cast(unsigned, b); }
; __device__ __forceinline__ v4i16_t vtr(LAS const char* p) { return __builtin_amdgcn_ds_read_tr16_b64_v4i16((LAS v4i16_t*)p); }
; #define MFMA32(a, b, c) __builtin_amdgcn_mfma_f32_32x32x16_bf16((a), (b), (c), 0, 0, 0)
; template <int DQK, int NSUB, int MODE>
; __device__ __forceinline__ void flash_unit(LAS char* L, const bf16_t* Qp, int qpitch, const bf16_t* Kp, int kpitch, const bf16_t* Vp, int vpitch,
;                                            bf16_t* Op, int opitch, float lam, float oscale, const float* subln) {
;     ...
; #pragma unroll
;                 for (int r = 0; r < 16; ++r) ph[r] = __builtin_amdgcn_exp2f(ph[r]);
;                 { typedef float f32x2_ __attribute__((ext_vector_type(2))); f32x2_ r2 = {ph[0], ph[1]};
; #pragma unroll
;                   for (int r = 2; r < 16; r += 2) r2 += (f32x2_){ph[r], ph[r + 1]};
;                   lrow[s] += r2[0] + r2[1]; }
;                 bf16x8 pf[2];
; #pragma unroll
;                 for (int k2 = 0; k2 < 2; ++k2) { u32x4 w;
; #pragma unroll
;                     for (int e = 0; e < 4; ++e) w[e] = cvt_pk_bf16(ph[8 * k2 + 2 * e], ph[8 * k2 + 2 * e + 1]);
;                     pf[k2] = __builtin_bit_cast(bf16x8, w); }
; #pragma unroll
;                 for (int db = 0; db < 2; ++db)
; #pragma unroll
;                     for (int k2 = 0; k2 < 2; ++k2) { const int ks = 2 * hf + k2; const v4i16_t lo = vtr(Vb + (16 * ks) * VPB + db * 64), hh = vtr(Vb + (16 * ks + 8) * VPB + db * 64);
;                         const bf16x8 vf = {lo[0], lo[1], lo[2], lo[3], hh[0], hh[1], hh[2], hh[3]};
;                         o[s][db] = MFMA32(vf, pf[k2], o[s][db]); }
.LBB0_585:
	v_exp_f32_e32 v112, v112
	v_exp_f32_e32 v113, v113
	v_exp_f32_e32 v114, v114
	v_exp_f32_e32 v115, v115
	v_exp_f32_e32 v116, v116
	v_exp_f32_e32 v117, v117
	v_exp_f32_e32 v118, v118
	v_exp_f32_e32 v119, v119
	v_exp_f32_e32 v120, v120
	v_exp_f32_e32 v121, v121
	v_exp_f32_e32 v122, v122
	v_exp_f32_e32 v123, v123
	v_pk_add_f32 v[196:197], v[112:113], v[114:115]
	v_cvt_pk_bf16_f32 v112, v112, v113
	v_pk_add_f32 v[196:197], v[116:117], v[196:197]
	v_cvt_pk_bf16_f32 v113, v114, v115
	v_pk_add_f32 v[196:197], v[118:119], v[196:197]
	v_cvt_pk_bf16_f32 v114, v116, v117
	v_pk_add_f32 v[196:197], v[120:121], v[196:197]
	v_cvt_pk_bf16_f32 v116, v120, v121
	v_pk_add_f32 v[196:197], v[122:123], v[196:197]
	v_cvt_pk_bf16_f32 v117, v122, v123
	ds_read_b64_tr_b16 v[120:121], v158 offset:18432
	ds_read_b64_tr_b16 v[122:123], v158 offset:19584
	v_cvt_pk_bf16_f32 v115, v118, v119
	v_exp_f32_e32 v124, v124
	v_exp_f32_e32 v125, v125
	s_waitcnt lgkmcnt(0)
	v_mfma_f32_32x32x16_bf16 v[48:63], v[120:123], v[112:115], v[48:63]
	v_exp_f32_e32 v126, v126
	v_exp_f32_e32 v127, v127
	ds_read_b64_tr_b16 v[120:121], v158 offset:20736
	ds_read_b64_tr_b16 v[122:123], v158 offset:21888
	v_cvt_pk_bf16_f32 v118, v124, v125
	v_pk_add_f32 v[196:197], v[124:125], v[196:197]
	v_cvt_pk_bf16_f32 v119, v126, v127
	v_pk_add_f32 v[196:197], v[126:127], v[196:197]
	s_waitcnt lgkmcnt(0)
	v_mfma_f32_32x32x16_bf16 v[48:63], v[120:123], v[116:119], v[48:63]
	ds_read_b64_tr_b16 v[120:121], v158 offset:18496
	ds_read_b64_tr_b16 v[122:123], v158 offset:19648
	v_add_f32_e32 v195, v196, v197
	s_waitcnt lgkmcnt(0)
	v_mfma_f32_32x32x16_bf16 v[64:79], v[120:123], v[112:115], v[64:79]
	ds_read_b64_tr_b16 v[112:113], v158 offset:20800
	ds_read_b64_tr_b16 v[114:115], v158 offset:21952
	s_waitcnt lgkmcnt(0)
	v_mfma_f32_32x32x16_bf16 v[64:79], v[112:115], v[116:119], v[64:79]
	v_max_f32_e32 v113, v97, v97
	v_max_f32_e32 v114, v96, v96
	v_max_f32_e32 v113, v114, v113
	v_max3_f32 v113, v113, v98, v99
	v_max3_f32 v113, v113, v100, v101
	v_max3_f32 v113, v113, v102, v103
	v_max3_f32 v113, v113, v104, v105
	v_max3_f32 v113, v113, v106, v107
	v_max3_f32 v113, v113, v108, v109
	v_max3_f32 v113, v113, v110, v111
	v_add_f32_e32 v112, v160, v195
	v_cmp_lt_f32_e32 vcc, s61, v113
	s_cbranch_vccz .LBB0_587
	ds_bpermute_b32 v114, v184, v113
	s_waitcnt lgkmcnt(0)
	v_max_f32_e32 v114, v114, v114
	v_max_f32_e32 v113, v113, v114
	v_max_f32_e32 v80, v113, v113
	v_max_f32_e32 v82, 0, v80
	v_exp_f32_e64 v84, -v82
	v_add_f32_e32 v161, v161, v82
	v_xor_b32_e32 v80, 0x80000000, v161
	v_pk_add_f32 v[96:97], v[96:97], v[82:83] op_sel_hi:[1,0] neg_lo:[0,1] neg_hi:[0,1]
	v_pk_add_f32 v[98:99], v[98:99], v[82:83] op_sel_hi:[1,0] neg_lo:[0,1] neg_hi:[0,1]
	v_pk_add_f32 v[100:101], v[100:101], v[82:83] op_sel_hi:[1,0] neg_lo:[0,1] neg_hi:[0,1]
	v_pk_add_f32 v[102:103], v[102:103], v[82:83] op_sel_hi:[1,0] neg_lo:[0,1] neg_hi:[0,1]
	v_pk_add_f32 v[104:105], v[104:105], v[82:83] op_sel_hi:[1,0] neg_lo:[0,1] neg_hi:[0,1]
	v_pk_add_f32 v[106:107], v[106:107], v[82:83] op_sel_hi:[1,0] neg_lo:[0,1] neg_hi:[0,1]
	v_pk_add_f32 v[108:109], v[108:109], v[82:83] op_sel_hi:[1,0] neg_lo:[0,1] neg_hi:[0,1]
	v_pk_add_f32 v[110:111], v[110:111], v[82:83] op_sel_hi:[1,0] neg_lo:[0,1] neg_hi:[0,1]
	v_pk_mul_f32 v[62:63], v[62:63], v[84:85] op_sel_hi:[1,0]
	v_pk_mul_f32 v[60:61], v[60:61], v[84:85] op_sel_hi:[1,0]
	v_pk_mul_f32 v[58:59], v[58:59], v[84:85] op_sel_hi:[1,0]
	v_pk_mul_f32 v[56:57], v[56:57], v[84:85] op_sel_hi:[1,0]
	v_pk_mul_f32 v[54:55], v[54:55], v[84:85] op_sel_hi:[1,0]
	v_pk_mul_f32 v[52:53], v[52:53], v[84:85] op_sel_hi:[1,0]
	v_pk_mul_f32 v[50:51], v[50:51], v[84:85] op_sel_hi:[1,0]
	v_pk_mul_f32 v[48:49], v[48:49], v[84:85] op_sel_hi:[1,0]
	v_pk_mul_f32 v[78:79], v[78:79], v[84:85] op_sel_hi:[1,0]
	v_pk_mul_f32 v[76:77], v[76:77], v[84:85] op_sel_hi:[1,0]
	v_pk_mul_f32 v[74:75], v[74:75], v[84:85] op_sel_hi:[1,0]
	v_pk_mul_f32 v[72:73], v[72:73], v[84:85] op_sel_hi:[1,0]
	v_pk_mul_f32 v[70:71], v[70:71], v[84:85] op_sel_hi:[1,0]
	v_pk_mul_f32 v[68:69], v[68:69], v[84:85] op_sel_hi:[1,0]
	v_pk_mul_f32 v[66:67], v[66:67], v[84:85] op_sel_hi:[1,0]
	v_pk_mul_f32 v[64:65], v[64:65], v[84:85] op_sel_hi:[1,0]
	v_mul_f32_e32 v112, v112, v84
	v_mov_b32_e32 v81, v80
	v_mov_b32_e32 v82, v80
	v_mov_b32_e32 v83, v80
	v_mov_b32_e32 v84, v80
	v_mov_b32_e32 v85, v80
	v_mov_b32_e32 v86, v80
	v_mov_b32_e32 v87, v80
	v_mov_b32_e32 v88, v80
	v_mov_b32_e32 v89, v80
	v_mov_b32_e32 v90, v80
	v_mov_b32_e32 v91, v80
	v_mov_b32_e32 v92, v80
	v_mov_b32_e32 v93, v80
	v_mov_b32_e32 v94, v80
	v_mov_b32_e32 v95, v80

; #define MFMA32(a, b, c) __builtin_amdgcn_mfma_f32_32x32x16_bf16((a), (b), (c), 0, 0, 0)
; template <int DQK, int NSUB, int MODE>
; __device__ __forceinline__ void flash_unit(LAS char* L, const bf16_t* Qp, int qpitch, const bf16_t* Kp, int kpitch, const bf16_t* Vp, int vpitch,
;                                            bf16_t* Op, int opitch, float lam, float oscale, const float* subln) {
;     ...
;         for (int s = 0; s < NSUB; ++s) {
;             f32x16 p0, p1;
; #pragma unroll
;             for (int d0 = 0; d0 < ND0; ++d0) { const bf16x8 k0 = *(const bf16x8*)(Kb + r32 * KPB + (s * DQK + 16 * d0 + 8 * hi) * 2); const bf16x8 k1 = *(const bf16x8*)(Kb + (32 + r32) * KPB + (s * DQK + 16 * d0 + 8 * hi) * 2);
;                 if (d0 == 0) { p0 = MFMA32(k0, qf[s][d0], negm[s]); p1 = MFMA32(k1, qf[s][d0], negm[s]); }
;                 else { p0 = MFMA32(k0, qf[s][d0], p0); p1 = MFMA32(k1, qf[s][d0], p1); } }
; #pragma unroll
;             for (int hf = 0; hf < 2; ++hf) {
;                 f32x16& ph = hf ? p1 : p0;
;                 float mx = fmaxf(ph[0], ph[1]);
; #pragma unroll
;                 for (int r = 2; r < 16; ++r) mx = fmaxf(mx, ph[r]);
;                 mx = fmaxf(mx, __shfl_xor(mx, 32));
;                 const bool first = (t == 0) && (hf == 0);
;                 if (first || __any(mx > 8.0f)) {
;                     const float dl = first ? mx : fmaxf(mx, 0.f); mref[s] += dl;
; #pragma unroll
;                     for (int r = 0; r < 16; ++r) { ph[r] -= dl; negm[s][r] = -mref[s]; }
;                     if (hf == 0) {
; #pragma unroll
;                         for (int r = 0; r < 16; ++r) p1[r] -= dl;
;                     }
;                     if (!first) { const float alpha = __builtin_amdgcn_exp2f(-dl); lrow[s] *= alpha;
; #pragma unroll
;                         for (int r = 0; r < 16; ++r) { o[s][0][r] *= alpha; o[s][1][r] *= alpha; } }
;                 }
.LBB0_612:
	s_and_b32 s8, s21, 1
	s_mul_i32 s9, s8, 0x3400
	v_add_u32_e32 v140, s9, v131
	ds_read_b128 v[132:135], v140 offset:6656
	ds_read_b128 v[48:51], v140
	ds_read_b128 v[136:139], v140 offset:32
	s_waitcnt lgkmcnt(0)
	v_mfma_f32_32x32x16_bf16 v[64:79], v[48:51], v[100:103], v[32:47]
	v_mov_b64_e32 v[62:63], v[46:47]
	v_mov_b64_e32 v[60:61], v[44:45]
	v_mov_b64_e32 v[58:59], v[42:43]
	v_mov_b64_e32 v[56:57], v[40:41]
	v_mov_b64_e32 v[54:55], v[38:39]
	v_mov_b64_e32 v[52:53], v[36:37]
	v_mov_b64_e32 v[50:51], v[34:35]
	v_mov_b64_e32 v[48:49], v[32:33]
	v_mfma_f32_32x32x16_bf16 v[64:79], v[136:139], v[80:83], v[64:79]
	s_nop 0
	v_mfma_f32_32x32x16_bf16 v[48:63], v[132:135], v[100:103], v[48:63]
	ds_read_b128 v[132:135], v140 offset:6688
	s_waitcnt lgkmcnt(0)
	v_mfma_f32_32x32x16_bf16 v[48:63], v[132:135], v[80:83], v[48:63]
	ds_read_b128 v[132:135], v140 offset:6720
	ds_read_b128 v[136:139], v140 offset:64
	s_waitcnt lgkmcnt(0)
	v_mfma_f32_32x32x16_bf16 v[64:79], v[136:139], v[84:87], v[64:79]
	v_mfma_f32_32x32x16_bf16 v[48:63], v[132:135], v[84:87], v[48:63]
	ds_read_b128 v[132:135], v140 offset:6752
	ds_read_b128 v[136:139], v140 offset:96
	s_waitcnt lgkmcnt(0)
	v_mfma_f32_32x32x16_bf16 v[64:79], v[136:139], v[88:91], v[64:79]
	v_mfma_f32_32x32x16_bf16 v[48:63], v[132:135], v[88:91], v[48:63]
	ds_read_b128 v[132:135], v140 offset:6784
	ds_read_b128 v[136:139], v140 offset:128
	s_waitcnt lgkmcnt(0)
	v_mfma_f32_32x32x16_bf16 v[64:79], v[136:139], v[92:95], v[64:79]
	v_mfma_f32_32x32x16_bf16 v[48:63], v[132:135], v[92:95], v[48:63]
	ds_read_b128 v[132:135], v140 offset:6816
	ds_read_b128 v[136:139], v140 offset:160
	s_waitcnt lgkmcnt(0)
	v_mfma_f32_32x32x16_bf16 v[64:79], v[136:139], v[96:99], v[64:79]
	v_mfma_f32_32x32x16_bf16 v[48:63], v[132:135], v[96:99], v[48:63]
	s_nop 10
	v_max_f32_e32 v132, v65, v65
	v_max_f32_e32 v133, v64, v64
	v_max_f32_e32 v132, v133, v132
	v_max3_f32 v132, v132, v66, v67
	v_max3_f32 v132, v132, v68, v69
	v_max3_f32 v132, v132, v70, v71
	v_max3_f32 v132, v132, v72, v73
	v_max3_f32 v132, v132, v74, v75
	v_max3_f32 v132, v132, v76, v77
	v_max3_f32 v132, v132, v78, v79
	v_cmp_lt_f32_e32 vcc, s61, v132
	s_cbranch_vccz .LBB0_614
	ds_bpermute_b32 v133, v184, v132
	s_waitcnt lgkmcnt(0)
	v_max_f32_e32 v133, v133, v133
	v_max_f32_e32 v132, v132, v133
	v_max_f32_e32 v32, v132, v132
	v_max_f32_e32 v33, 0, v32
	v_exp_f32_e64 v34, -v33
	v_add_f32_e32 v119, v119, v33
	v_xor_b32_e32 v32, 0x80000000, v119
	v_sub_f32_e32 v79, v79, v33
	v_sub_f32_e32 v78, v78, v33
	v_sub_f32_e32 v77, v77, v33
	v_sub_f32_e32 v76, v76, v33
	v_sub_f32_e32 v75, v75, v33
	v_sub_f32_e32 v74, v74, v33
	v_sub_f32_e32 v73, v73, v33
	v_sub_f32_e32 v72, v72, v33
	v_sub_f32_e32 v71, v71, v33
	v_sub_f32_e32 v70, v70, v33
	v_sub_f32_e32 v69, v69, v33
	v_sub_f32_e32 v68, v68, v33
	v_sub_f32_e32 v67, v67, v33
	v_sub_f32_e32 v66, v66, v33
	v_sub_f32_e32 v65, v65, v33
	v_sub_f32_e32 v64, v64, v33
	v_sub_f32_e32 v63, v63, v33
	v_sub_f32_e32 v62, v62, v33
	v_sub_f32_e32 v61, v61, v33
	v_sub_f32_e32 v60, v60, v33
	v_sub_f32_e32 v59, v59, v33
	v_sub_f32_e32 v58, v58, v33
	v_sub_f32_e32 v57, v57, v33
	v_sub_f32_e32 v56, v56, v33
	v_sub_f32_e32 v55, v55, v33
	v_sub_f32_e32 v54, v54, v33
	v_sub_f32_e32 v53, v53, v33
	v_sub_f32_e32 v52, v52, v33
	v_sub_f32_e32 v51, v51, v33
	v_sub_f32_e32 v50, v50, v33
	v_sub_f32_e32 v49, v49, v33
	v_sub_f32_e32 v48, v48, v33
	v_pk_mul_f32 v[30:31], v[30:31], v[34:35] op_sel_hi:[1,0]
	v_pk_mul_f32 v[28:29], v[28:29], v[34:35] op_sel_hi:[1,0]
	v_pk_mul_f32 v[26:27], v[26:27], v[34:35] op_sel_hi:[1,0]
	v_pk_mul_f32 v[24:25], v[24:25], v[34:35] op_sel_hi:[1,0]
	v_pk_mul_f32 v[22:23], v[22:23], v[34:35] op_sel_hi:[1,0]
	v_pk_mul_f32 v[20:21], v[20:21], v[34:35] op_sel_hi:[1,0]
	v_pk_mul_f32 v[18:19], v[18:19], v[34:35] op_sel_hi:[1,0]
	v_pk_mul_f32 v[16:17], v[16:17], v[34:35] op_sel_hi:[1,0]
	v_pk_mul_f32 v[14:15], v[14:15], v[34:35] op_sel_hi:[1,0]
	v_pk_mul_f32 v[12:13], v[12:13], v[34:35] op_sel_hi:[1,0]
	v_pk_mul_f32 v[10:11], v[10:11], v[34:35] op_sel_hi:[1,0]
	v_pk_mul_f32 v[8:9], v[8:9], v[34:35] op_sel_hi:[1,0]
	v_pk_mul_f32 v[6:7], v[6:7], v[34:35] op_sel_hi:[1,0]
	v_pk_mul_f32 v[4:5], v[4:5], v[34:35] op_sel_hi:[1,0]
	v_pk_mul_f32 v[2:3], v[2:3], v[34:35] op_sel_hi:[1,0]
	v_pk_mul_f32 v[0:1], v[0:1], v[34:35] op_sel_hi:[1,0]
	v_mul_f32_e32 v118, v118, v34
	v_mov_b32_e32 v33, v32
	v_mov_b32_e32 v34, v32
	v_mov_b32_e32 v35, v32
	v_mov_b32_e32 v36, v32
	v_mov_b32_e32 v37, v32
	v_mov_b32_e32 v38, v32
	v_mov_b32_e32 v39, v32
	v_mov_b32_e32 v40, v32
	v_mov_b32_e32 v41, v32
	v_mov_b32_e32 v42, v32
	v_mov_b32_e32 v43, v32
	v_mov_b32_e32 v44, v32
	v_mov_b32_e32 v45, v32
	v_mov_b32_e32 v46, v32
	v_mov_b32_e32 v47, v32
; template <int DQK, int NSUB, int MODE>
; __device__ __forceinline__ void flash_unit(LAS char* L, const bf16_t* Qp, int qpitch, const bf16_t* Kp, int kpitch, const bf16_t* Vp, int vpitch,
;                                            bf16_t* Op, int opitch, float lam, float oscale, const float* subln) {
;     ...
;             for (int hf = 0; hf < 2; ++hf) {
;                 f32x16& ph = hf ? p1 : p0;
;                 float mx = fmaxf(ph[0], ph[1]);
; #pragma unroll
;                 for (int r = 2; r < 16; ++r) mx = fmaxf(mx, ph[r]);
;                 mx = fmaxf(mx, __shfl_xor(mx, 32));
;                 const bool first = (t == 0) && (hf == 0);
;                 if (first || __any(mx > 8.0f)) {
;                     const float dl = first ? mx : fmaxf(mx, 0.f); mref[s] += dl;
; #pragma unroll
;                     for (int r = 0; r < 16; ++r) { ph[r] -= dl; negm[s][r] = -mref[s]; }
;                     if (hf == 0) {
; #pragma unroll
;                         for (int r = 0; r < 16; ++r) p1[r] -= dl;
;                     }
;                     if (!first) { const float alpha = __builtin_amdgcn_exp2f(-dl); lrow[s] *= alpha;
; #pragma unroll
;                         for (int r = 0; r < 16; ++r) { o[s][0][r] *= alpha; o[s][1][r] *= alpha; } }
;                 }
; #pragma unroll
;                 for (int r = 0; r < 16; ++r) ph[r] = __builtin_amdgcn_exp2f(ph[r]);
;                 { typedef float f32x2_ __attribute__((ext_vector_type(2))); f32x2_ r2 = {ph[0], ph[1]};
; #pragma unroll
;                   for (int r = 2; r < 16; r += 2) r2 += (f32x2_){ph[r], ph[r + 1]};
;                   lrow[s] += r2[0] + r2[1]; }
;                 bf16x8 pf[2];
; #pragma unroll
;                 for (int k2 = 0; k2 < 2; ++k2) { u32x4 w;
; #pragma unroll
;                     for (int e = 0; e < 4; ++e) w[e] = cvt_pk_bf16(ph[8 * k2 + 2 * e], ph[8 * k2 + 2 * e + 1]);
;                     pf[k2] = __builtin_bit_cast(bf16x8, w); }
; #pragma unroll
;                 for (int db = 0; db < 2; ++db)
; #pragma unroll
;                     for (int k2 = 0; k2 < 2; ++k2) { const int ks = 2 * hf + k2; const v4i16_t lo = vtr(Vb + (16 * ks) * VPB + db * 64), hh = vtr(Vb + (16 * ks + 8) * VPB + db * 64);
;                         const bf16x8 vf = {lo[0], lo[1], lo[2], lo[3], hh[0], hh[1], hh[2], hh[3]};
;                         o[s][db] = MFMA32(vf, pf[k2], o[s][db]); }
.LBB0_614:
	v_exp_f32_e32 v64, v64
	v_exp_f32_e32 v65, v65
	v_exp_f32_e32 v132, v66
	v_exp_f32_e32 v133, v67
	v_exp_f32_e32 v68, v68
	v_exp_f32_e32 v69, v69
	v_exp_f32_e32 v70, v70
	v_exp_f32_e32 v71, v71
	v_exp_f32_e32 v72, v72
	v_exp_f32_e32 v73, v73
	v_exp_f32_e32 v74, v74
	v_exp_f32_e32 v75, v75
	v_pk_add_f32 v[66:67], v[64:65], v[132:133]
	v_exp_f32_e32 v76, v76
	v_exp_f32_e32 v77, v77
	v_pk_add_f32 v[66:67], v[68:69], v[66:67]
	v_exp_f32_e32 v78, v78
	v_exp_f32_e32 v79, v79
	v_pk_add_f32 v[66:67], v[70:71], v[66:67]
	s_mul_i32 s9, s8, 0x2400
	v_pk_add_f32 v[66:67], v[72:73], v[66:67]
	v_cvt_pk_bf16_f32 v68, v68, v69
	v_pk_add_f32 v[66:67], v[74:75], v[66:67]
	v_cvt_pk_bf16_f32 v69, v70, v71
	v_pk_add_f32 v[66:67], v[76:77], v[66:67]
	v_cvt_pk_bf16_f32 v70, v72, v73
	v_pk_add_f32 v[134:135], v[78:79], v[66:67]
	v_cvt_pk_bf16_f32 v66, v64, v65
	v_add_u32_e32 v64, s9, v130
	v_cvt_pk_bf16_f32 v71, v74, v75
	v_cvt_pk_bf16_f32 v72, v76, v77
	ds_read_b64_tr_b16 v[74:75], v64 offset:26624
	ds_read_b64_tr_b16 v[76:77], v64 offset:27776
	v_cvt_pk_bf16_f32 v67, v132, v133
	v_cvt_pk_bf16_f32 v73, v78, v79
	v_add_f32_e32 v65, v134, v135
	s_waitcnt lgkmcnt(0)
	v_mfma_f32_32x32x16_bf16 v[0:15], v[74:77], v[66:69], v[0:15]
	ds_read_b64_tr_b16 v[74:75], v64 offset:28928
	ds_read_b64_tr_b16 v[76:77], v64 offset:30080
	v_add_f32_e32 v65, v118, v65
	s_waitcnt lgkmcnt(0)
	v_mfma_f32_32x32x16_bf16 v[0:15], v[74:77], v[70:73], v[0:15]
	ds_read_b64_tr_b16 v[74:75], v64 offset:26688
	ds_read_b64_tr_b16 v[76:77], v64 offset:27840
	s_waitcnt lgkmcnt(0)
	v_mfma_f32_32x32x16_bf16 v[16:31], v[74:77], v[66:69], v[16:31]
	ds_read_b64_tr_b16 v[66:67], v64 offset:28992
	ds_read_b64_tr_b16 v[68:69], v64 offset:30144
	s_waitcnt lgkmcnt(0)
	v_mfma_f32_32x32x16_bf16 v[16:31], v[66:69], v[70:73], v[16:31]
	v_max_f32_e32 v66, v49, v49
	v_max_f32_e32 v67, v48, v48
	v_max_f32_e32 v66, v67, v66
	v_max3_f32 v66, v66, v50, v51
	v_max3_f32 v66, v66, v52, v53
	v_max3_f32 v66, v66, v54, v55
	v_max3_f32 v66, v66, v56, v57
	v_max3_f32 v66, v66, v58, v59
	v_max3_f32 v66, v66, v60, v61
	v_max3_f32 v66, v66, v62, v63
	v_cmp_lt_f32_e32 vcc, s61, v66
	s_cbranch_vccz .LBB0_616
	ds_bpermute_b32 v67, v184, v66
	s_waitcnt lgkmcnt(0)
	v_max_f32_e32 v67, v67, v67
	v_max_f32_e32 v66, v66, v67
	v_max_f32_e32 v32, v66, v66
	v_max_f32_e32 v33, 0, v32
	v_exp_f32_e64 v34, -v33
	v_add_f32_e32 v119, v119, v33
	v_xor_b32_e32 v32, 0x80000000, v119
	v_sub_f32_e32 v63, v63, v33
	v_sub_f32_e32 v62, v62, v33
	v_sub_f32_e32 v61, v61, v33
	v_sub_f32_e32 v60, v60, v33
	v_sub_f32_e32 v59, v59, v33
	v_sub_f32_e32 v58, v58, v33
	v_sub_f32_e32 v57, v57, v33
	v_sub_f32_e32 v56, v56, v33
	v_sub_f32_e32 v55, v55, v33
	v_sub_f32_e32 v54, v54, v33
	v_sub_f32_e32 v53, v53, v33
	v_sub_f32_e32 v52, v52, v33
	v_sub_f32_e32 v51, v51, v33
	v_sub_f32_e32 v50, v50, v33
	v_sub_f32_e32 v49, v49, v33
	v_sub_f32_e32 v48, v48, v33
	v_pk_mul_f32 v[14:15], v[14:15], v[34:35] op_sel_hi:[1,0]
	v_pk_mul_f32 v[12:13], v[12:13], v[34:35] op_sel_hi:[1,0]
	v_pk_mul_f32 v[10:11], v[10:11], v[34:35] op_sel_hi:[1,0]
	v_pk_mul_f32 v[8:9], v[8:9], v[34:35] op_sel_hi:[1,0]
	v_pk_mul_f32 v[6:7], v[6:7], v[34:35] op_sel_hi:[1,0]
	v_pk_mul_f32 v[4:5], v[4:5], v[34:35] op_sel_hi:[1,0]
	v_pk_mul_f32 v[2:3], v[2:3], v[34:35] op_sel_hi:[1,0]
	v_pk_mul_f32 v[0:1], v[0:1], v[34:35] op_sel_hi:[1,0]
	v_pk_mul_f32 v[30:31], v[30:31], v[34:35] op_sel_hi:[1,0]
	v_pk_mul_f32 v[28:29], v[28:29], v[34:35] op_sel_hi:[1,0]
	v_pk_mul_f32 v[26:27], v[26:27], v[34:35] op_sel_hi:[1,0]
	v_pk_mul_f32 v[24:25], v[24:25], v[34:35] op_sel_hi:[1,0]
	v_pk_mul_f32 v[22:23], v[22:23], v[34:35] op_sel_hi:[1,0]
	v_pk_mul_f32 v[20:21], v[20:21], v[34:35] op_sel_hi:[1,0]
	v_pk_mul_f32 v[18:19], v[18:19], v[34:35] op_sel_hi:[1,0]
	v_pk_mul_f32 v[16:17], v[16:17], v[34:35] op_sel_hi:[1,0]
	v_mul_f32_e32 v65, v65, v34
	v_mov_b32_e32 v33, v32
	v_mov_b32_e32 v34, v32
	v_mov_b32_e32 v35, v32
	v_mov_b32_e32 v36, v32
	v_mov_b32_e32 v37, v32
	v_mov_b32_e32 v38, v32
	v_mov_b32_e32 v39, v32
	v_mov_b32_e32 v40, v32
	v_mov_b32_e32 v41, v32
	v_mov_b32_e32 v42, v32
	v_mov_b32_e32 v43, v32
	v_mov_b32_e32 v44, v32
	v_mov_b32_e32 v45, v32
	v_mov_b32_e32 v46, v32
	v_mov_b32_e32 v47, v32

; #define LAS __attribute__((address_space(3)))
; #define MFMA32(a, b, c) __builtin_amdgcn_mfma_f32_32x32x16_bf16((a), (b), (c), 0, 0, 0)
; template <int DQK, int NSUB, int MODE>
; __device__ __forceinline__ void flash_unit(LAS char* L, const bf16_t* Qp, int qpitch, const bf16_t* Kp, int kpitch, const bf16_t* Vp, int vpitch,
;                                            bf16_t* Op, int opitch, float lam, float oscale, const float* subln) {
;     ...
;         if (t + 1 < SEQ / 64) { const size_t ko = (size_t)(t + 1) * 64 * kpitch, vo = (size_t)(t + 1) * 64 * vpitch;
;             rk1 = *(const u32x4*)(kg1 + ko); if (has2) rk2 = *(const u32x4*)(kg2 + ko); rv1 = *(const u32x4*)(vg1 + vo); }
;         const char* Kb = Lg + buf * KBUF; LAS const char* Vb = L + OFF_V + buf * VBUF + voff;
; #pragma unroll
;         for (int s = 0; s < NSUB; ++s) {
;             f32x16 p0, p1;
; #pragma unroll
;             for (int d0 = 0; d0 < ND0; ++d0) { const bf16x8 k0 = *(const bf16x8*)(Kb + r32 * KPB + (s * DQK + 16 * d0 + 8 * hi) * 2); const bf16x8 k1 = *(const bf16x8*)(Kb + (32 + r32) * KPB + (s * DQK + 16 * d0 + 8 * hi) * 2);
;                 if (d0 == 0) { p0 = MFMA32(k0, qf[s][d0], negm[s]); p1 = MFMA32(k1, qf[s][d0], negm[s]); }
;                 else { p0 = MFMA32(k0, qf[s][d0], p0); p1 = MFMA32(k1, qf[s][d0], p1); } }
; #pragma unroll
;             for (int hf = 0; hf < 2; ++hf) {
;                 f32x16& ph = hf ? p1 : p0;
;                 float mx = fmaxf(ph[0], ph[1]);
; #pragma unroll
;                 for (int r = 2; r < 16; ++r) mx = fmaxf(mx, ph[r]);
;                 mx = fmaxf(mx, __shfl_xor(mx, 32));
;                 const bool first = (t == 0) && (hf == 0);
;                 if (first || __any(mx > 8.0f)) {
;                     const float dl = first ? mx : fmaxf(mx, 0.f); mref[s] += dl;
; #pragma unroll
;                     for (int r = 0; r < 16; ++r) { ph[r] -= dl; negm[s][r] = -mref[s]; }
;                     if (hf == 0) {
; #pragma unroll
;                         for (int r = 0; r < 16; ++r) p1[r] -= dl;
;                     }
;                     if (!first) { const float alpha = __builtin_amdgcn_exp2f(-dl); lrow[s] *= alpha;
; #pragma unroll
;                         for (int r = 0; r < 16; ++r) { o[s][0][r] *= alpha; o[s][1][r] *= alpha; } }
;                 }
.LBB0_636:
	v_lshl_add_u64 v[222:223], v[132:133], 0, s[10:11]
	global_load_dwordx4 v[120:123], v[222:223], off
	s_and_saveexec_b64 s[8:9], s[36:37]
	s_cbranch_execz .Lfd_638
	v_lshl_add_u64 v[222:223], v[130:131], 0, s[10:11]
	global_load_dwordx4 v[112:115], v[222:223], off
.Lfd_638:
	s_or_b64 exec, exec, s[8:9]
	v_lshl_add_u64 v[222:223], v[128:129], 0, s[10:11]
	global_load_dwordx4 v[116:119], v[222:223], off
	s_and_b32 s8, s14, 1
	s_mul_i32 s9, s8, 0x2400
	v_add_u32_e32 v224, s9, v139
	v_add_u32_e32 v220, s9, v135
	ds_read_b128 v[32:35], v224
	ds_read_b128 v[36:39], v224 offset:32
	ds_read_b128 v[40:43], v224 offset:64
	ds_read_b128 v[44:47], v224 offset:96
	ds_read_b128 v[144:147], v224 offset:4608
	ds_read_b128 v[148:151], v224 offset:4640
	ds_read_b128 v[152:155], v224 offset:4672
	ds_read_b128 v[164:167], v224 offset:4704
	s_waitcnt lgkmcnt(4)
	v_mfma_f32_32x32x16_bf16 v[80:95], v[32:35], v[108:111], v[48:63]
	v_mfma_f32_32x32x16_bf16 v[80:95], v[36:39], v[104:107], v[80:95]
	v_mfma_f32_32x32x16_bf16 v[80:95], v[40:43], v[100:103], v[80:95]
	v_mfma_f32_32x32x16_bf16 v[80:95], v[44:47], v[96:99], v[80:95]
	s_waitcnt lgkmcnt(0)
	v_mfma_f32_32x32x16_bf16 v[64:79], v[144:147], v[108:111], v[48:63]
	v_mfma_f32_32x32x16_bf16 v[64:79], v[148:151], v[104:107], v[64:79]
	ds_read_b64_tr_b16 v[204:205], v220 offset:18432
	ds_read_b64_tr_b16 v[206:207], v220 offset:19584
	ds_read_b64_tr_b16 v[208:209], v220 offset:20736
	ds_read_b64_tr_b16 v[210:211], v220 offset:21888
	ds_read_b64_tr_b16 v[212:213], v220 offset:18496
	ds_read_b64_tr_b16 v[214:215], v220 offset:19648
	ds_read_b64_tr_b16 v[216:217], v220 offset:20800
	ds_read_b64_tr_b16 v[218:219], v220 offset:21952
	ds_read_b64_tr_b16 v[168:169], v220 offset:23040
	ds_read_b64_tr_b16 v[170:171], v220 offset:24192
	ds_read_b64_tr_b16 v[172:173], v220 offset:25344
	ds_read_b64_tr_b16 v[174:175], v220 offset:26496
	ds_read_b64_tr_b16 v[176:177], v220 offset:23104
	ds_read_b64_tr_b16 v[178:179], v220 offset:24256
	ds_read_b64_tr_b16 v[180:181], v220 offset:25408
	ds_read_b64_tr_b16 v[182:183], v220 offset:26560
	v_max_f32_e32 v222, v81, v81
	v_max_f32_e32 v223, v80, v80
	v_max_f32_e32 v222, v223, v222
	v_mfma_f32_32x32x16_bf16 v[64:79], v[152:155], v[100:103], v[64:79]
	v_max3_f32 v222, v222, v82, v83
	v_max3_f32 v222, v222, v84, v85
	v_max3_f32 v222, v222, v86, v87
	v_max3_f32 v222, v222, v88, v89
	v_mfma_f32_32x32x16_bf16 v[64:79], v[164:167], v[96:99], v[64:79]
	v_max3_f32 v222, v222, v90, v91
	v_max3_f32 v222, v222, v92, v93
	v_max3_f32 v222, v222, v94, v95
	v_cmp_lt_f32_e32 vcc, s61, v222
	s_cbranch_vccz .Lfd_641
	ds_bpermute_b32 v223, v184, v222
	s_waitcnt lgkmcnt(0)
	v_max_f32_e32 v223, v223, v223
	v_max_f32_e32 v222, v222, v223
	v_max_f32_e32 v222, v222, v222
	v_max_f32_e32 v223, 0, v222
	v_exp_f32_e64 v224, -v223
	v_add_f32_e32 v127, v127, v223
	v_xor_b32_e32 v222, 0x80000000, v127
	v_sub_f32_e32 v95, v95, v223
	v_sub_f32_e32 v94, v94, v223
	v_sub_f32_e32 v93, v93, v223
	v_sub_f32_e32 v92, v92, v223
	v_sub_f32_e32 v91, v91, v223
	v_sub_f32_e32 v90, v90, v223
	v_sub_f32_e32 v89, v89, v223
	v_sub_f32_e32 v88, v88, v223
	v_sub_f32_e32 v87, v87, v223
	v_sub_f32_e32 v86, v86, v223
	v_sub_f32_e32 v85, v85, v223
	v_sub_f32_e32 v84, v84, v223
	v_sub_f32_e32 v83, v83, v223
	v_sub_f32_e32 v82, v82, v223
	v_sub_f32_e32 v81, v81, v223
	v_sub_f32_e32 v80, v80, v223
	v_sub_f32_e32 v79, v79, v223
	v_sub_f32_e32 v78, v78, v223
	v_sub_f32_e32 v77, v77, v223
	v_sub_f32_e32 v76, v76, v223
	v_sub_f32_e32 v75, v75, v223
	v_sub_f32_e32 v74, v74, v223
	v_sub_f32_e32 v73, v73, v223
	v_sub_f32_e32 v72, v72, v223
	v_sub_f32_e32 v71, v71, v223
	v_sub_f32_e32 v70, v70, v223
	v_sub_f32_e32 v69, v69, v223
	v_sub_f32_e32 v68, v68, v223
	v_sub_f32_e32 v67, v67, v223
	v_sub_f32_e32 v66, v66, v223
	v_sub_f32_e32 v65, v65, v223
	v_sub_f32_e32 v64, v64, v223
	v_pk_mul_f32 v[30:31], v[30:31], v[224:225] op_sel_hi:[1,0]
	v_pk_mul_f32 v[28:29], v[28:29], v[224:225] op_sel_hi:[1,0]
	v_pk_mul_f32 v[26:27], v[26:27], v[224:225] op_sel_hi:[1,0]
	v_pk_mul_f32 v[24:25], v[24:25], v[224:225] op_sel_hi:[1,0]
	v_pk_mul_f32 v[22:23], v[22:23], v[224:225] op_sel_hi:[1,0]
	v_pk_mul_f32 v[20:21], v[20:21], v[224:225] op_sel_hi:[1,0]
	v_pk_mul_f32 v[18:19], v[18:19], v[224:225] op_sel_hi:[1,0]
	v_pk_mul_f32 v[16:17], v[16:17], v[224:225] op_sel_hi:[1,0]
	v_pk_mul_f32 v[14:15], v[14:15], v[224:225] op_sel_hi:[1,0]
	v_pk_mul_f32 v[12:13], v[12:13], v[224:225] op_sel_hi:[1,0]
	v_pk_mul_f32 v[10:11], v[10:11], v[224:225] op_sel_hi:[1,0]
	v_pk_mul_f32 v[8:9], v[8:9], v[224:225] op_sel_hi:[1,0]
	v_pk_mul_f32 v[6:7], v[6:7], v[224:225] op_sel_hi:[1,0]
	v_pk_mul_f32 v[4:5], v[4:5], v[224:225] op_sel_hi:[1,0]
	v_pk_mul_f32 v[2:3], v[2:3], v[224:225] op_sel_hi:[1,0]
	v_pk_mul_f32 v[0:1], v[0:1], v[224:225] op_sel_hi:[1,0]
	v_mul_f32_e32 v126, v126, v224
	v_mov_b32_e32 v48, v222
	v_mov_b32_e32 v49, v222
	v_mov_b32_e32 v50, v222
	v_mov_b32_e32 v51, v222
	v_mov_b32_e32 v52, v222
	v_mov_b32_e32 v53, v222
	v_mov_b32_e32 v54, v222
	v_mov_b32_e32 v55, v222
	v_mov_b32_e32 v56, v222
	v_mov_b32_e32 v57, v222
	v_mov_b32_e32 v58, v222
	v_mov_b32_e32 v59, v222
	v_mov_b32_e32 v60, v222
	v_mov_b32_e32 v61, v222
	v_mov_b32_e32 v62, v222
	v_mov_b32_e32 v63, v222
; __device__ __forceinline__ unsigned cvt_pk_bf16(float lo, float hi) { typedef float f2 __attribute__((ext_vector_type(2))); typedef __bf16 b2 __attribute__((ext_vector_type(2))); f2 v = {lo, hi}; b2 b = __builtin_convertvector(v, b2); return __builtin_bit_cast(unsigned, b); }
; __device__ __forceinline__ v4i16_t vtr(LAS const char* p) { return __builtin_amdgcn_ds_read_tr16_b64_v4i16((LAS v4i16_t*)p); }
; #define MFMA32(a, b, c) __builtin_amdgcn_mfma_f32_32x32x16_bf16((a), (b), (c), 0, 0, 0)
; template <int DQK, int NSUB, int MODE>
; __device__ __forceinline__ void flash_unit(LAS char* L, const bf16_t* Qp, int qpitch, const bf16_t* Kp, int kpitch, const bf16_t* Vp, int vpitch,
;                                            bf16_t* Op, int opitch, float lam, float oscale, const float* subln) {
;     ...
; #pragma unroll
;                 for (int r = 0; r < 16; ++r) ph[r] = __builtin_amdgcn_exp2f(ph[r]);
;                 { typedef float f32x2_ __attribute__((ext_vector_type(2))); f32x2_ r2 = {ph[0], ph[1]};
; #pragma unroll
;                   for (int r = 2; r < 16; r += 2) r2 += (f32x2_){ph[r], ph[r + 1]};
;                   lrow[s] += r2[0] + r2[1]; }
;                 bf16x8 pf[2];
; #pragma unroll
;                 for (int k2 = 0; k2 < 2; ++k2) { u32x4 w;
; #pragma unroll
;                     for (int e = 0; e < 4; ++e) w[e] = cvt_pk_bf16(ph[8 * k2 + 2 * e], ph[8 * k2 + 2 * e + 1]);
;                     pf[k2] = __builtin_bit_cast(bf16x8, w); }
; #pragma unroll
;                 for (int db = 0; db < 2; ++db)
; #pragma unroll
;                     for (int k2 = 0; k2 < 2; ++k2) { const int ks = 2 * hf + k2; const v4i16_t lo = vtr(Vb + (16 * ks) * VPB + db * 64), hh = vtr(Vb + (16 * ks + 8) * VPB + db * 64);
;                         const bf16x8 vf = {lo[0], lo[1], lo[2], lo[3], hh[0], hh[1], hh[2], hh[3]};
;                         o[s][db] = MFMA32(vf, pf[k2], o[s][db]); }
;             }
;         }
;         if (t + 1 < SEQ / 64) { char* Kn = Lg + (buf ^ 1) * KBUF; *(u32x4*)(Kn + kl1) = rk1; if (has2) *(u32x4*)(Kn + kl2) = rk2; *(u32x4*)(Lg + OFF_V + (buf ^ 1) * VBUF + vl1) = rv1; }
.Lfd_641:
	v_exp_f32_e32 v80, v80
	v_exp_f32_e32 v81, v81
	v_exp_f32_e32 v140, v82
	v_exp_f32_e32 v141, v83
	v_exp_f32_e32 v84, v84
	v_exp_f32_e32 v85, v85
	v_exp_f32_e32 v86, v86
	v_exp_f32_e32 v87, v87
	v_exp_f32_e32 v88, v88
	v_exp_f32_e32 v89, v89
	v_exp_f32_e32 v90, v90
	v_exp_f32_e32 v91, v91
	v_pk_add_f32 v[82:83], v[80:81], v[140:141]
	v_exp_f32_e32 v92, v92
	v_exp_f32_e32 v93, v93
	v_pk_add_f32 v[82:83], v[84:85], v[82:83]
	v_exp_f32_e32 v94, v94
	v_exp_f32_e32 v95, v95
	v_pk_add_f32 v[82:83], v[86:87], v[82:83]
	v_cvt_pk_bf16_f32 v84, v84, v85
	v_pk_add_f32 v[82:83], v[88:89], v[82:83]
	v_cvt_pk_bf16_f32 v85, v86, v87
	v_pk_add_f32 v[82:83], v[90:91], v[82:83]
	v_cvt_pk_bf16_f32 v86, v88, v89
	v_pk_add_f32 v[82:83], v[92:93], v[82:83]
	v_cvt_pk_bf16_f32 v87, v90, v91
	v_pk_add_f32 v[142:143], v[94:95], v[82:83]
	v_cvt_pk_bf16_f32 v82, v80, v81
	v_cvt_pk_bf16_f32 v88, v92, v93
	v_cvt_pk_bf16_f32 v83, v140, v141
	v_cvt_pk_bf16_f32 v89, v94, v95
	v_add_f32_e32 v81, v142, v143
	s_waitcnt lgkmcnt(0)
	v_mfma_f32_32x32x16_bf16 v[0:15], v[204:207], v[82:85], v[0:15]
	v_add_f32_e32 v81, v126, v81
	v_max_f32_e32 v224, v65, v65
	v_max_f32_e32 v225, v64, v64
	v_max_f32_e32 v224, v225, v224
	v_mfma_f32_32x32x16_bf16 v[0:15], v[208:211], v[86:89], v[0:15]
	v_max3_f32 v224, v224, v66, v67
	v_max3_f32 v224, v224, v68, v69
	v_max3_f32 v224, v224, v70, v71
	v_max3_f32 v224, v224, v72, v73
	v_mfma_f32_32x32x16_bf16 v[16:31], v[212:215], v[82:85], v[16:31]
	v_max3_f32 v224, v224, v74, v75
	v_max3_f32 v224, v224, v76, v77
	v_max3_f32 v224, v224, v78, v79
	v_mfma_f32_32x32x16_bf16 v[16:31], v[216:219], v[86:89], v[16:31]
	v_cmp_lt_f32_e32 vcc, s61, v224
	s_cbranch_vccz .Lfd_643
	ds_bpermute_b32 v225, v184, v224
	s_waitcnt lgkmcnt(0)
	v_max_f32_e32 v225, v225, v225
	v_max_f32_e32 v224, v224, v225
	v_max_f32_e32 v222, v224, v224
	v_max_f32_e32 v223, 0, v222
	v_exp_f32_e64 v224, -v223
	v_add_f32_e32 v127, v127, v223
	v_xor_b32_e32 v222, 0x80000000, v127
	v_sub_f32_e32 v79, v79, v223
	v_sub_f32_e32 v78, v78, v223
	v_sub_f32_e32 v77, v77, v223
	v_sub_f32_e32 v76, v76, v223
	v_sub_f32_e32 v75, v75, v223
	v_sub_f32_e32 v74, v74, v223
	v_sub_f32_e32 v73, v73, v223
	v_sub_f32_e32 v72, v72, v223
	v_sub_f32_e32 v71, v71, v223
	v_sub_f32_e32 v70, v70, v223
	v_sub_f32_e32 v69, v69, v223
	v_sub_f32_e32 v68, v68, v223
	v_sub_f32_e32 v67, v67, v223
	v_sub_f32_e32 v66, v66, v223
	v_sub_f32_e32 v65, v65, v223
	v_sub_f32_e32 v64, v64, v223
	v_pk_mul_f32 v[14:15], v[14:15], v[224:225] op_sel_hi:[1,0]
	v_pk_mul_f32 v[12:13], v[12:13], v[224:225] op_sel_hi:[1,0]
	v_pk_mul_f32 v[10:11], v[10:11], v[224:225] op_sel_hi:[1,0]
	v_pk_mul_f32 v[8:9], v[8:9], v[224:225] op_sel_hi:[1,0]
	v_pk_mul_f32 v[6:7], v[6:7], v[224:225] op_sel_hi:[1,0]
	v_pk_mul_f32 v[4:5], v[4:5], v[224:225] op_sel_hi:[1,0]
	v_pk_mul_f32 v[2:3], v[2:3], v[224:225] op_sel_hi:[1,0]
	v_pk_mul_f32 v[0:1], v[0:1], v[224:225] op_sel_hi:[1,0]
	v_pk_mul_f32 v[30:31], v[30:31], v[224:225] op_sel_hi:[1,0]
	v_pk_mul_f32 v[28:29], v[28:29], v[224:225] op_sel_hi:[1,0]
	v_pk_mul_f32 v[26:27], v[26:27], v[224:225] op_sel_hi:[1,0]
	v_pk_mul_f32 v[24:25], v[24:25], v[224:225] op_sel_hi:[1,0]
	v_pk_mul_f32 v[22:23], v[22:23], v[224:225] op_sel_hi:[1,0]
	v_pk_mul_f32 v[20:21], v[20:21], v[224:225] op_sel_hi:[1,0]
	v_pk_mul_f32 v[18:19], v[18:19], v[224:225] op_sel_hi:[1,0]
	v_pk_mul_f32 v[16:17], v[16:17], v[224:225] op_sel_hi:[1,0]
	v_mul_f32_e32 v81, v81, v224
	v_mov_b32_e32 v48, v222
	v_mov_b32_e32 v49, v222
	v_mov_b32_e32 v50, v222
	v_mov_b32_e32 v51, v222
	v_mov_b32_e32 v52, v222
	v_mov_b32_e32 v53, v222
	v_mov_b32_e32 v54, v222
	v_mov_b32_e32 v55, v222
	v_mov_b32_e32 v56, v222
	v_mov_b32_e32 v57, v222
	v_mov_b32_e32 v58, v222
	v_mov_b32_e32 v59, v222
	v_mov_b32_e32 v60, v222
	v_mov_b32_e32 v61, v222
	v_mov_b32_e32 v62, v222
	v_mov_b32_e32 v63, v222
.Lfd_643:
	v_exp_f32_e32 v64, v64
	v_exp_f32_e32 v65, v65
	v_exp_f32_e32 v66, v66
	v_exp_f32_e32 v67, v67
	v_exp_f32_e32 v68, v68
	v_exp_f32_e32 v69, v69
	v_exp_f32_e32 v70, v70
	v_exp_f32_e32 v71, v71
	v_cvt_pk_bf16_f32 v82, v64, v65
	v_cvt_pk_bf16_f32 v83, v66, v67
	v_cvt_pk_bf16_f32 v84, v68, v69
	v_cvt_pk_bf16_f32 v85, v70, v71
	v_exp_f32_e32 v72, v72
	v_exp_f32_e32 v73, v73
	v_mfma_f32_32x32x16_bf16 v[0:15], v[168:171], v[82:85], v[0:15]
	v_exp_f32_e32 v74, v74
	v_exp_f32_e32 v75, v75
	v_exp_f32_e32 v76, v76
	v_exp_f32_e32 v77, v77
	v_exp_f32_e32 v78, v78
	v_exp_f32_e32 v79, v79
	v_cvt_pk_bf16_f32 v86, v72, v73
	v_cvt_pk_bf16_f32 v87, v74, v75
	v_cvt_pk_bf16_f32 v88, v76, v77
	v_cvt_pk_bf16_f32 v89, v78, v79
	s_xor_b32 s15, s8, 1
	s_mulk_i32 s15, 0x2400
	v_mfma_f32_32x32x16_bf16 v[0:15], v[172:175], v[86:89], v[0:15]
	s_add_i32 s16, s15, 0
	v_mfma_f32_32x32x16_bf16 v[16:31], v[176:179], v[82:85], v[16:31]
	v_add_u32_e32 v80, s16, v137
	s_waitcnt vmcnt(0)
	ds_write_b128 v80, v[120:123]
	v_mfma_f32_32x32x16_bf16 v[16:31], v[180:183], v[86:89], v[16:31]
	s_and_saveexec_b64 s[8:9], s[36:37]
	s_cbranch_execz .LBB0_635
	v_add_u32_e32 v80, s16, v136
	ds_write_b128 v80, v[112:115]
	s_branch .LBB0_635

; __device__ __forceinline__ void natten_unit(LAS char* L, const bf16_t* Pseq  , bf16_t* Oseq  , int h, int r0, const float* rpb) {
;     ...
;     int rs_lo = r0 - 4; rs_lo = rs_lo < 0 ? 0 : (rs_lo > 24 ? 24 : rs_lo);
;     int rs_hi = r0 + 3 - 4; rs_hi = rs_hi < 0 ? 0 : (rs_hi > 24 ? 24 : rs_hi);
;     const int nst = (rs_hi - rs_lo + 8) * 64 * 8;
;     __syncthreads();
;     {   const bf16_t* vsrc = Pseq + (size_t)(rs_lo * 64) * PPITCH + PB + 512 + h * 64;
; #pragma unroll
;         for (int i = 0; i < 11; ++i) { const int c = tid + 512 * i; if (c < nst) { const int row = c >> 3, ch = c & 7; *(u32x4*)(Lg + row * VPB + ch * 16) = *(const u32x4*)(vsrc + (size_t)row * PPITCH + ch * 8); } }
;         if (tid < 465) rpbL[tid] = rpb[h * 465 + tid] * LOG2E;
;     }
.LBB0_651:
	s_ashr_i32 s12, s31, 5
	s_lshl_b32 s8, s31, 2
	s_mov_b64 s[10:11], s[86:87]
	s_bfe_u32 s14, s31, 0x20003
	s_and_b32 s33, s8, 28
	s_mul_i32 s9, s12, 0xa00000
	s_mul_hi_i32 s8, s12, 0xa00000
	s_add_u32 s9, s10, s9
	s_addc_u32 s8, s11, s8
	v_sub_u32_e64 v19, s33, 4 clamp
	s_add_u32 s38, s9, 0x84c8000
	v_med3_u32 v0, s33, 1, 25
	v_not_b32_e32 v2, v19
	s_addc_u32 s39, s8, 0
	v_mov_b32_e32 v1, v240
	v_add_u32_e32 v0, v0, v2
	v_mul_lo_u32 v192, v19, s18
	v_lshlrev_b32_e32 v5, 9, v0
	v_lshl_add_u64 v[2:3], s[38:39], 0, v[192:193]
	s_lshl_b32 s16, s14, 7
	v_lshlrev_b32_e32 v0, 4, v1
	v_add_u32_e32 v4, 0x1000, v5
	v_lshl_add_u64 v[2:3], v[2:3], 0, s[16:17]
	v_and_b32_e32 v192, 0x70, v0
	v_lshl_add_u64 v[2:3], v[2:3], 0, v[192:193]
	v_add_u32_e32 v0, 0, v192
	v_cmp_lt_i32_e32 vcc, v1, v4
	s_waitcnt lgkmcnt(0)
	s_barrier
	v_mov_b32_e32 v6, v1
	v_cmp_lt_i32_e32 vcc, v6, v4
	s_and_saveexec_b64 s[8:9], vcc
	s_cbranch_execz .Lnat_ld_0
	v_ashrrev_i32_e32 v10, 3, v6
	v_mad_i64_i32 v[6:7], s[20:21], v10, s56, v[2:3]
	global_load_dwordx4 v[100:103], v[6:7], off offset:2560
.Lnat_ld_0:
	s_or_b64 exec, exec, s[8:9]
	v_add_u32_e32 v6, 0x200, v1
	v_cmp_lt_i32_e32 vcc, v6, v4
	s_and_saveexec_b64 s[8:9], vcc
	s_cbranch_execz .Lnat_ld_1
	v_ashrrev_i32_e32 v10, 3, v6
	v_mad_i64_i32 v[6:7], s[20:21], v10, s56, v[2:3]
	global_load_dwordx4 v[104:107], v[6:7], off offset:2560
.Lnat_ld_1:
	s_or_b64 exec, exec, s[8:9]
	v_add_u32_e32 v6, 0x400, v1
	v_cmp_lt_i32_e32 vcc, v6, v4
	s_and_saveexec_b64 s[8:9], vcc
	s_cbranch_execz .Lnat_ld_2
	v_ashrrev_i32_e32 v10, 3, v6
	v_mad_i64_i32 v[6:7], s[20:21], v10, s56, v[2:3]
	global_load_dwordx4 v[108:111], v[6:7], off offset:2560
.Lnat_ld_2:
	s_or_b64 exec, exec, s[8:9]
	v_add_u32_e32 v6, 0x600, v1
	v_cmp_lt_i32_e32 vcc, v6, v4
	s_and_saveexec_b64 s[8:9], vcc
	s_cbranch_execz .Lnat_ld_3
	v_ashrrev_i32_e32 v10, 3, v6
	v_mad_i64_i32 v[6:7], s[20:21], v10, s56, v[2:3]
	global_load_dwordx4 v[112:115], v[6:7], off offset:2560
.Lnat_ld_3:
	s_or_b64 exec, exec, s[8:9]
	v_add_u32_e32 v6, 0x800, v1
	v_cmp_lt_i32_e32 vcc, v6, v4
	s_and_saveexec_b64 s[8:9], vcc
	s_cbranch_execz .Lnat_ld_4
	v_ashrrev_i32_e32 v10, 3, v6
	v_mad_i64_i32 v[6:7], s[20:21], v10, s56, v[2:3]
	global_load_dwordx4 v[116:119], v[6:7], off offset:2560
.Lnat_ld_4:
	s_or_b64 exec, exec, s[8:9]
	v_add_u32_e32 v6, 0xa00, v1
	v_cmp_lt_i32_e32 vcc, v6, v4
	s_and_saveexec_b64 s[8:9], vcc
	s_cbranch_execz .Lnat_ld_5
	v_ashrrev_i32_e32 v10, 3, v6
	v_mad_i64_i32 v[6:7], s[20:21], v10, s56, v[2:3]
	global_load_dwordx4 v[120:123], v[6:7], off offset:2560
.Lnat_ld_5:
	s_or_b64 exec, exec, s[8:9]
	v_add_u32_e32 v6, 0xc00, v1
	v_cmp_lt_i32_e32 vcc, v6, v4
	s_and_saveexec_b64 s[8:9], vcc
	s_cbranch_execz .Lnat_ld_6
	v_ashrrev_i32_e32 v10, 3, v6
	v_mad_i64_i32 v[6:7], s[20:21], v10, s56, v[2:3]
	global_load_dwordx4 v[124:127], v[6:7], off offset:2560
.Lnat_ld_6:
	s_or_b64 exec, exec, s[8:9]
	v_add_u32_e32 v6, 0xe00, v1
	v_cmp_lt_i32_e32 vcc, v6, v4
	s_and_saveexec_b64 s[8:9], vcc
	s_cbranch_execz .Lnat_ld_7
	v_ashrrev_i32_e32 v10, 3, v6
	v_mad_i64_i32 v[6:7], s[20:21], v10, s56, v[2:3]
	global_load_dwordx4 v[128:131], v[6:7], off offset:2560
.Lnat_ld_7:
	s_or_b64 exec, exec, s[8:9]
	v_add_u32_e32 v6, 0x1000, v1
	v_cmp_lt_i32_e32 vcc, v6, v4
	s_and_saveexec_b64 s[8:9], vcc
	s_cbranch_execz .Lnat_ld_8
	v_ashrrev_i32_e32 v10, 3, v6
	v_mad_i64_i32 v[6:7], s[20:21], v10, s56, v[2:3]
	global_load_dwordx4 v[132:135], v[6:7], off offset:2560
; __device__ __forceinline__ void natten_unit(LAS char* L, const bf16_t* Pseq  , bf16_t* Oseq  , int h, int r0, const float* rpb) {
;     ...
;     {   const bf16_t* vsrc = Pseq + (size_t)(rs_lo * 64) * PPITCH + PB + 512 + h * 64;
; #pragma unroll
;         for (int i = 0; i < 11; ++i) { const int c = tid + 512 * i; if (c < nst) { const int row = c >> 3, ch = c & 7; *(u32x4*)(Lg + row * VPB + ch * 16) = *(const u32x4*)(vsrc + (size_t)row * PPITCH + ch * 8); } }
;         if (tid < 465) rpbL[tid] = rpb[h * 465 + tid] * LOG2E;
;     }
;     __syncthreads();
.Lnat_ld_8:
	s_or_b64 exec, exec, s[8:9]
	v_add_u32_e32 v6, 0x1200, v1
	v_cmp_lt_i32_e32 vcc, v6, v4
	s_and_saveexec_b64 s[8:9], vcc
	s_cbranch_execz .Lnat_ld_9
	v_ashrrev_i32_e32 v10, 3, v6
	v_mad_i64_i32 v[6:7], s[20:21], v10, s56, v[2:3]
	global_load_dwordx4 v[136:139], v[6:7], off offset:2560
.Lnat_ld_9:
	s_or_b64 exec, exec, s[8:9]
	v_add_u32_e32 v6, 0x1400, v1
	v_cmp_lt_i32_e32 vcc, v6, v4
	s_and_saveexec_b64 s[8:9], vcc
	s_cbranch_execz .Lnat_ld_10
	v_ashrrev_i32_e32 v10, 3, v6
	v_mad_i64_i32 v[6:7], s[20:21], v10, s56, v[2:3]
	global_load_dwordx4 v[140:143], v[6:7], off offset:2560
.Lnat_ld_10:
	s_or_b64 exec, exec, s[8:9]
	s_waitcnt vmcnt(0)
	v_mov_b32_e32 v6, v1
	v_cmp_lt_i32_e32 vcc, v6, v4
	s_and_saveexec_b64 s[8:9], vcc
	s_cbranch_execz .Lnat_st_0
	v_ashrrev_i32_e32 v10, 3, v6
	v_mad_u64_u32 v[10:11], s[20:21], v10, s27, v[0:1]
	ds_write_b128 v10, v[100:103]
.Lnat_st_0:
	s_or_b64 exec, exec, s[8:9]
	v_add_u32_e32 v6, 0x200, v1
	v_cmp_lt_i32_e32 vcc, v6, v4
	s_and_saveexec_b64 s[8:9], vcc
	s_cbranch_execz .Lnat_st_1
	v_ashrrev_i32_e32 v10, 3, v6
	v_mad_u64_u32 v[10:11], s[20:21], v10, s27, v[0:1]
	ds_write_b128 v10, v[104:107]
.Lnat_st_1:
	s_or_b64 exec, exec, s[8:9]
	v_add_u32_e32 v6, 0x400, v1
	v_cmp_lt_i32_e32 vcc, v6, v4
	s_and_saveexec_b64 s[8:9], vcc
	s_cbranch_execz .Lnat_st_2
	v_ashrrev_i32_e32 v10, 3, v6
	v_mad_u64_u32 v[10:11], s[20:21], v10, s27, v[0:1]
	ds_write_b128 v10, v[108:111]
.Lnat_st_2:
	s_or_b64 exec, exec, s[8:9]
	v_add_u32_e32 v6, 0x600, v1
	v_cmp_lt_i32_e32 vcc, v6, v4
	s_and_saveexec_b64 s[8:9], vcc
	s_cbranch_execz .Lnat_st_3
	v_ashrrev_i32_e32 v10, 3, v6
	v_mad_u64_u32 v[10:11], s[20:21], v10, s27, v[0:1]
	ds_write_b128 v10, v[112:115]
.Lnat_st_3:
	s_or_b64 exec, exec, s[8:9]
	v_add_u32_e32 v6, 0x800, v1
	v_cmp_lt_i32_e32 vcc, v6, v4
	s_and_saveexec_b64 s[8:9], vcc
	s_cbranch_execz .Lnat_st_4
	v_ashrrev_i32_e32 v10, 3, v6
	v_mad_u64_u32 v[10:11], s[20:21], v10, s27, v[0:1]
	ds_write_b128 v10, v[116:119]
.Lnat_st_4:
	s_or_b64 exec, exec, s[8:9]
	v_add_u32_e32 v6, 0xa00, v1
	v_cmp_lt_i32_e32 vcc, v6, v4
	s_and_saveexec_b64 s[8:9], vcc
	s_cbranch_execz .Lnat_st_5
	v_ashrrev_i32_e32 v10, 3, v6
	v_mad_u64_u32 v[10:11], s[20:21], v10, s27, v[0:1]
	ds_write_b128 v10, v[120:123]
.Lnat_st_5:
	s_or_b64 exec, exec, s[8:9]
	v_add_u32_e32 v6, 0xc00, v1
	v_cmp_lt_i32_e32 vcc, v6, v4
	s_and_saveexec_b64 s[8:9], vcc
	s_cbranch_execz .Lnat_st_6
	v_ashrrev_i32_e32 v10, 3, v6
	v_mad_u64_u32 v[10:11], s[20:21], v10, s27, v[0:1]
	ds_write_b128 v10, v[124:127]
.Lnat_st_6:
	s_or_b64 exec, exec, s[8:9]
	v_add_u32_e32 v6, 0xe00, v1
	v_cmp_lt_i32_e32 vcc, v6, v4
	s_and_saveexec_b64 s[8:9], vcc
	s_cbranch_execz .Lnat_st_7
	v_ashrrev_i32_e32 v10, 3, v6
	v_mad_u64_u32 v[10:11], s[20:21], v10, s27, v[0:1]
	ds_write_b128 v10, v[128:131]
.Lnat_st_7:
	s_or_b64 exec, exec, s[8:9]
	v_add_u32_e32 v6, 0x1000, v1
	v_cmp_lt_i32_e32 vcc, v6, v4
	s_and_saveexec_b64 s[8:9], vcc
	s_cbranch_execz .Lnat_st_8
	v_ashrrev_i32_e32 v10, 3, v6
	v_mad_u64_u32 v[10:11], s[20:21], v10, s27, v[0:1]
	ds_write_b128 v10, v[132:135]
.Lnat_st_8:
	s_or_b64 exec, exec, s[8:9]
	v_add_u32_e32 v6, 0x1200, v1
	v_cmp_lt_i32_e32 vcc, v6, v4
	s_and_saveexec_b64 s[8:9], vcc
	s_cbranch_execz .Lnat_st_9
	v_ashrrev_i32_e32 v10, 3, v6
	v_mad_u64_u32 v[10:11], s[20:21], v10, s27, v[0:1]
	ds_write_b128 v10, v[136:139]
.Lnat_st_9:
	s_or_b64 exec, exec, s[8:9]
	v_add_u32_e32 v6, 0x1400, v1
	v_cmp_lt_i32_e32 vcc, v6, v4
	s_and_saveexec_b64 s[8:9], vcc
	s_cbranch_execz .Lnat_st_10
	v_ashrrev_i32_e32 v10, 3, v6
	v_mad_u64_u32 v[10:11], s[20:21], v10, s27, v[0:1]
	ds_write_b128 v10, v[140:143]

; __device__ __forceinline__ unsigned cvt_pk_bf16(float lo, float hi) { typedef float f2 __attribute__((ext_vector_type(2))); typedef __bf16 b2 __attribute__((ext_vector_type(2))); f2 v = {lo, hi}; b2 b = __builtin_convertvector(v, b2); return __builtin_bit_cast(unsigned, b); }
; #define LAS __attribute__((address_space(3)))
; __device__ __forceinline__ v4i16_t vtr(LAS const char* p) { return __builtin_amdgcn_ds_read_tr16_b64_v4i16((LAS v4i16_t*)p); }
; #define MFMA16(a, b, c) __builtin_amdgcn_mfma_f32_16x16x32_bf16((a), (b), (c), 0, 0, 0)
; __device__ __forceinline__ void natten_unit(LAS char* L, const bf16_t* Pseq  , bf16_t* Oseq  , int h, int r0, const float* rpb) {
;     ...
;         float mx = -INFINITY;
; #pragma unroll
;         for (int t = 0; t < 16; ++t) mx = fmaxf(mx, fmaxf(fmaxf(sc[t][0], sc[t][1]), fmaxf(sc[t][2], sc[t][3])));
;         mx = fmaxf(mx, __shfl_xor(mx, 16)); mx = fmaxf(mx, __shfl_xor(mx, 32));
;         float sum = 0.f;
; #pragma unroll
;         for (int t = 0; t < 16; ++t)
; #pragma unroll
;             for (int j = 0; j < 4; ++j) { const float e = __builtin_amdgcn_exp2f(sc[t][j] - mx); sc[t][j] = e; sum += e; }
;         sum += __shfl_xor(sum, 16); sum += __shfl_xor(sum, 32);
;         const float inv = 1.0f / sum;
;         f32x4 o[4];
; #pragma unroll
;         for (int dt = 0; dt < 4; ++dt) o[dt] = (f32x4){0.f, 0.f, 0.f, 0.f};
;         LAS const char* Vb = L + (size_t)((rs - rs_lo) * 64 + cb + 4 * quad + (m >> 2)) * VPB + (lane & 3) * 8;
; #pragma unroll
;         for (int u = 0; u < 8; ++u) { u32x4 w; w.x = cvt_pk_bf16(sc[2 * u][0], sc[2 * u][1]); w.y = cvt_pk_bf16(sc[2 * u][2], sc[2 * u][3]);
;             w.z = cvt_pk_bf16(sc[2 * u + 1][0], sc[2 * u + 1][1]); w.w = cvt_pk_bf16(sc[2 * u + 1][2], sc[2 * u + 1][3]);
;             const bf16x8 pf = __builtin_bit_cast(bf16x8, w);
; #pragma unroll
;             for (int dt = 0; dt < 4; ++dt) { const v4i16_t lo = vtr(Vb + (u * 64) * VPB + dt * 32), hh = vtr(Vb + (u * 64 + 16) * VPB + dt * 32);
;                 const bf16x8 vf = {lo[0], lo[1], lo[2], lo[3], hh[0], hh[1], hh[2], hh[3]};
;                 o[dt] = MFMA16(vf, pf, o[dt]); } }
.LBB0_676:
	s_or_b64 exec, exec, s[8:9]
	v_max_f32_e32 v2, v36, v36
	v_max_f32_e32 v3, v37, v37
	v_max_f32_e32 v2, v3, v2
	v_max_f32_e32 v3, v40, v40
	v_max_f32_e32 v6, v41, v41
	v_max_f32_e32 v3, v6, v3
	v_max3_f32 v2, v35, v34, v2
	v_max3_f32 v3, v39, v38, v3
	s_mov_b32 s8, 0xff800000
	v_max3_f32 v2, v2, s8, v3
	v_max_f32_e32 v3, v44, v44
	v_max_f32_e32 v6, v45, v45
	v_max_f32_e32 v3, v6, v3
	v_max_f32_e32 v6, v49, v49
	v_max_f32_e32 v7, v50, v50
	v_max_f32_e32 v6, v7, v6
	v_max3_f32 v3, v43, v42, v3
	v_max3_f32 v6, v47, v46, v6
	v_max3_f32 v2, v2, v3, v6
	v_max_f32_e32 v3, v55, v55
	v_max_f32_e32 v6, v56, v56
	v_max_f32_e32 v3, v6, v3
	v_max_f32_e32 v6, v59, v59
	v_max_f32_e32 v7, v60, v60
	v_max_f32_e32 v6, v7, v6
	v_max3_f32 v3, v53, v52, v3
	v_max3_f32 v6, v58, v57, v6
	v_max3_f32 v2, v2, v3, v6
	v_max_f32_e32 v3, v64, v64
	v_max_f32_e32 v6, v66, v66
	v_max_f32_e32 v3, v6, v3
	v_max_f32_e32 v6, v70, v70
	v_max_f32_e32 v7, v71, v71
	v_max_f32_e32 v6, v7, v6
	v_max3_f32 v3, v62, v61, v3
	v_max3_f32 v6, v69, v68, v6
	v_max3_f32 v2, v2, v3, v6
	v_max_f32_e32 v3, v76, v76
	v_max_f32_e32 v6, v77, v77
	v_max_f32_e32 v3, v6, v3
	v_max_f32_e32 v6, v80, v80
	v_max_f32_e32 v7, v81, v81
	v_max_f32_e32 v6, v7, v6
	v_max3_f32 v3, v74, v73, v3
	v_max3_f32 v6, v79, v78, v6
	v_max3_f32 v2, v2, v3, v6
	v_max_f32_e32 v3, v84, v84
	v_max_f32_e32 v6, v85, v85
	v_max_f32_e32 v3, v6, v3
	v_max_f32_e32 v6, v88, v88
	v_max_f32_e32 v7, v89, v89
	v_max_f32_e32 v6, v7, v6
	v_max3_f32 v3, v83, v82, v3
	v_max3_f32 v6, v87, v86, v6
	v_max3_f32 v2, v2, v3, v6
	v_max_f32_e32 v3, v72, v72
	v_max_f32_e32 v6, v75, v75
	v_max_f32_e32 v3, v6, v3
	v_max_f32_e32 v6, v54, v54
	v_max_f32_e32 v7, v67, v67
	v_max_f32_e32 v6, v7, v6
	v_max3_f32 v3, v91, v90, v3
	v_max3_f32 v6, v65, v63, v6
	v_max3_f32 v2, v2, v3, v6
	v_max_f32_e32 v3, v8, v8
	v_max_f32_e32 v6, v9, v9
	v_max_f32_e32 v3, v6, v3
	v_max_f32_e32 v6, v0, v0
	v_max_f32_e32 v7, v1, v1
	v_max_f32_e32 v6, v7, v6
	v_max3_f32 v3, v51, v48, v3
	v_max3_f32 v6, v5, v4, v6
	v_max3_f32 v2, v2, v3, v6
	ds_bpermute_b32 v3, v18, v2
	s_xor_b64 s[38:39], s[38:39], -1
	s_waitcnt lgkmcnt(0)
	v_max_f32_e32 v3, v3, v3
	v_max_f32_e32 v2, v2, v3
	ds_bpermute_b32 v3, v184, v2
	s_waitcnt lgkmcnt(0)
	v_max_f32_e32 v3, v3, v3
	v_max_f32_e32 v2, v2, v3
	v_sub_f32_e32 v3, v35, v2
	v_exp_f32_e32 v99, v3
	v_sub_f32_e32 v3, v34, v2
	v_exp_f32_e32 v100, v3
	v_sub_f32_e32 v3, v37, v2
	v_exp_f32_e32 v101, v3
	v_sub_f32_e32 v3, v36, v2
	v_exp_f32_e32 v102, v3
	v_sub_f32_e32 v6, v39, v2
	v_add_f32_e32 v3, 0, v99
	v_exp_f32_e32 v103, v6
	v_sub_f32_e32 v6, v38, v2
	v_add_f32_e32 v3, v100, v3
	v_exp_f32_e32 v104, v6
	v_sub_f32_e32 v6, v41, v2
	v_add_f32_e32 v3, v101, v3
	v_exp_f32_e32 v105, v6
	v_sub_f32_e32 v6, v40, v2
	v_add_f32_e32 v3, v102, v3
	v_exp_f32_e32 v106, v6
	v_sub_f32_e32 v6, v43, v2
	v_add_f32_e32 v3, v103, v3
	v_exp_f32_e32 v107, v6
	v_sub_f32_e32 v6, v42, v2
	v_add_f32_e32 v3, v104, v3
	v_exp_f32_e32 v108, v6
	v_sub_f32_e32 v6, v45, v2
	v_add_f32_e32 v3, v105, v3
	v_exp_f32_e32 v109, v6
	v_sub_f32_e32 v6, v44, v2
	v_add_f32_e32 v3, v106, v3
	v_exp_f32_e32 v110, v6
	v_sub_f32_e32 v6, v47, v2
	v_add_f32_e32 v3, v107, v3
	v_exp_f32_e32 v111, v6
	v_sub_f32_e32 v6, v46, v2
	v_add_f32_e32 v3, v108, v3
	v_exp_f32_e32 v112, v6
	v_sub_f32_e32 v6, v50, v2
	v_add_f32_e32 v3, v109, v3
	v_exp_f32_e32 v113, v6
	v_sub_f32_e32 v6, v49, v2
	v_add_f32_e32 v3, v110, v3
	v_exp_f32_e32 v114, v6
	v_sub_f32_e32 v6, v53, v2
	v_add_f32_e32 v3, v111, v3
	v_exp_f32_e32 v92, v6
	v_sub_f32_e32 v6, v52, v2
	v_add_f32_e32 v3, v112, v3
	v_exp_f32_e32 v93, v6
	v_sub_f32_e32 v6, v56, v2
	v_add_f32_e32 v3, v113, v3
	v_exp_f32_e32 v95, v6
	v_sub_f32_e32 v6, v55, v2
	v_add_f32_e32 v3, v114, v3
	v_exp_f32_e32 v97, v6
	v_sub_f32_e32 v6, v58, v2
	v_add_f32_e32 v3, v92, v3
	v_exp_f32_e32 v94, v6
	v_sub_f32_e32 v6, v57, v2
	v_add_f32_e32 v3, v93, v3
	v_exp_f32_e32 v96, v6
	v_sub_f32_e32 v6, v60, v2
	v_add_f32_e32 v3, v95, v3
	v_exp_f32_e32 v60, v6
	v_sub_f32_e32 v6, v59, v2
	v_add_f32_e32 v3, v97, v3
	v_exp_f32_e32 v98, v6
	v_sub_f32_e32 v6, v62, v2
	v_add_f32_e32 v3, v94, v3
	v_exp_f32_e32 v49, v6
	v_sub_f32_e32 v6, v61, v2
	v_add_f32_e32 v3, v96, v3
	v_exp_f32_e32 v50, v6
	v_sub_f32_e32 v6, v66, v2
	v_add_f32_e32 v3, v60, v3
	v_exp_f32_e32 v53, v6
	v_sub_f32_e32 v6, v64, v2
	v_add_f32_e32 v3, v98, v3
	v_exp_f32_e32 v57, v6
	v_sub_f32_e32 v6, v69, v2
	v_add_f32_e32 v3, v49, v3
	v_exp_f32_e32 v52, v6
	v_sub_f32_e32 v6, v68, v2
	v_add_f32_e32 v3, v50, v3
	v_exp_f32_e32 v55, v6
	v_sub_f32_e32 v6, v71, v2
	v_add_f32_e32 v3, v53, v3
	v_exp_f32_e32 v56, v6
	v_sub_f32_e32 v6, v70, v2
	v_add_f32_e32 v3, v57, v3
	v_exp_f32_e32 v58, v6
	v_sub_f32_e32 v6, v74, v2
	v_add_f32_e32 v3, v52, v3
	v_exp_f32_e32 v39, v6
	v_sub_f32_e32 v6, v73, v2
	v_add_f32_e32 v3, v55, v3
	v_exp_f32_e32 v40, v6
	v_sub_f32_e32 v6, v77, v2
	v_add_f32_e32 v3, v56, v3
	v_exp_f32_e32 v42, v6
	v_sub_f32_e32 v6, v76, v2
	v_add_f32_e32 v3, v58, v3
	v_exp_f32_e32 v45, v6
	v_sub_f32_e32 v6, v79, v2
	v_add_f32_e32 v3, v39, v3
	v_exp_f32_e32 v41, v6
	v_sub_f32_e32 v6, v78, v2
	v_add_f32_e32 v3, v40, v3
	v_exp_f32_e32 v43, v6
	v_sub_f32_e32 v6, v81, v2
	v_add_f32_e32 v3, v42, v3
	v_exp_f32_e32 v44, v6
	v_sub_f32_e32 v6, v80, v2
	v_add_f32_e32 v3, v45, v3
	v_exp_f32_e32 v46, v6
	v_sub_f32_e32 v6, v83, v2
	v_add_f32_e32 v3, v41, v3
	v_exp_f32_e32 v7, v6
	v_sub_f32_e32 v6, v82, v2
	v_add_f32_e32 v3, v43, v3
	v_exp_f32_e32 v11, v6
	v_sub_f32_e32 v6, v85, v2
	v_add_f32_e32 v3, v44, v3
	v_exp_f32_e32 v36, v6
	v_sub_f32_e32 v6, v84, v2
	v_add_f32_e32 v3, v46, v3
	v_exp_f32_e32 v38, v6
	v_sub_f32_e32 v6, v87, v2
	v_add_f32_e32 v3, v7, v3
	v_exp_f32_e32 v10, v6
	v_sub_f32_e32 v6, v86, v2
	v_add_f32_e32 v3, v11, v3
	v_exp_f32_e32 v34, v6
	v_sub_f32_e32 v6, v89, v2
	v_add_f32_e32 v3, v36, v3
	v_exp_f32_e32 v35, v6
	v_sub_f32_e32 v6, v88, v2
	v_add_f32_e32 v3, v38, v3
	v_exp_f32_e32 v37, v6
	v_add_f32_e32 v3, v10, v3
	v_add_f32_e32 v3, v34, v3
	v_add_f32_e32 v3, v35, v3
	v_add_f32_e32 v59, v37, v3
	v_sub_f32_e32 v3, v91, v2
	v_exp_f32_e32 v6, v3
	v_sub_u32_e32 v3, v17, v19
	v_lshl_add_u32 v3, v3, 6, v23
	v_sub_f32_e32 v47, v90, v2
	v_mad_i32_i24 v3, v3, s27, v24
	ds_read_b64_tr_b16 v[70:71], v3 offset:2304
	ds_read_b64_tr_b16 v[68:69], v3
	ds_read_b64_tr_b16 v[80:81], v3 offset:32
	ds_read_b64_tr_b16 v[82:83], v3 offset:2336
	ds_read_b64_tr_b16 v[84:85], v3 offset:64
	ds_read_b64_tr_b16 v[86:87], v3 offset:2368
	v_exp_f32_e32 v17, v47
	ds_read_b64_tr_b16 v[88:89], v3 offset:96
	ds_read_b64_tr_b16 v[90:91], v3 offset:2400
	v_sub_f32_e32 v47, v75, v2
	v_exp_f32_e32 v47, v47
	v_add_f32_e32 v59, v6, v59
	v_cvt_pk_bf16_f32 v76, v99, v100
	v_cvt_pk_bf16_f32 v77, v101, v102
	v_cvt_pk_bf16_f32 v78, v103, v104
	v_cvt_pk_bf16_f32 v79, v105, v106
	v_add_f32_e32 v59, v17, v59
	v_add_f32_e32 v61, v47, v59
	s_waitcnt lgkmcnt(6)
; __device__ __forceinline__ unsigned cvt_pk_bf16(float lo, float hi) { typedef float f2 __attribute__((ext_vector_type(2))); typedef __bf16 b2 __attribute__((ext_vector_type(2))); f2 v = {lo, hi}; b2 b = __builtin_convertvector(v, b2); return __builtin_bit_cast(unsigned, b); }
; #define LAS __attribute__((address_space(3)))
; __device__ __forceinline__ v4i16_t vtr(LAS const char* p) { return __builtin_amdgcn_ds_read_tr16_b64_v4i16((LAS v4i16_t*)p); }
; #define MFMA16(a, b, c) __builtin_amdgcn_mfma_f32_16x16x32_bf16((a), (b), (c), 0, 0, 0)
; __device__ __forceinline__ void natten_unit(LAS char* L, const bf16_t* Pseq  , bf16_t* Oseq  , int h, int r0, const float* rpb) {
;     ...
;         f32x4 o[4];
; #pragma unroll
;         for (int dt = 0; dt < 4; ++dt) o[dt] = (f32x4){0.f, 0.f, 0.f, 0.f};
;         LAS const char* Vb = L + (size_t)((rs - rs_lo) * 64 + cb + 4 * quad + (m >> 2)) * VPB + (lane & 3) * 8;
; #pragma unroll
;         for (int u = 0; u < 8; ++u) { u32x4 w; w.x = cvt_pk_bf16(sc[2 * u][0], sc[2 * u][1]); w.y = cvt_pk_bf16(sc[2 * u][2], sc[2 * u][3]);
;             w.z = cvt_pk_bf16(sc[2 * u + 1][0], sc[2 * u + 1][1]); w.w = cvt_pk_bf16(sc[2 * u + 1][2], sc[2 * u + 1][3]);
;             const bf16x8 pf = __builtin_bit_cast(bf16x8, w);
; #pragma unroll
;             for (int dt = 0; dt < 4; ++dt) { const v4i16_t lo = vtr(Vb + (u * 64) * VPB + dt * 32), hh = vtr(Vb + (u * 64 + 16) * VPB + dt * 32);
;                 const bf16x8 vf = {lo[0], lo[1], lo[2], lo[3], hh[0], hh[1], hh[2], hh[3]};
;                 o[dt] = MFMA16(vf, pf, o[dt]); } }
	v_mfma_f32_16x16x32_bf16 v[68:71], v[68:71], v[76:79], 0
	v_sub_f32_e32 v59, v72, v2
	v_exp_f32_e32 v59, v59
	v_sub_f32_e32 v62, v63, v2
	s_waitcnt lgkmcnt(4)
	v_mfma_f32_16x16x32_bf16 v[80:83], v[80:83], v[76:79], 0
	v_sub_f32_e32 v63, v67, v2
	v_add_f32_e32 v99, v59, v61
	v_sub_f32_e32 v61, v65, v2
	s_waitcnt lgkmcnt(2)
	v_mfma_f32_16x16x32_bf16 v[84:87], v[84:87], v[76:79], 0
	v_exp_f32_e32 v61, v61
	v_exp_f32_e32 v62, v62
	v_sub_f32_e32 v54, v54, v2
	s_waitcnt lgkmcnt(0)
	v_mfma_f32_16x16x32_bf16 v[72:75], v[88:91], v[76:79], 0
	ds_read_b64_tr_b16 v[76:77], v3 offset:9216
	ds_read_b64_tr_b16 v[78:79], v3 offset:11520
	v_cvt_pk_bf16_f32 v88, v107, v108
	v_cvt_pk_bf16_f32 v89, v109, v110
	v_cvt_pk_bf16_f32 v90, v111, v112
	v_cvt_pk_bf16_f32 v91, v113, v114
	ds_read_b64_tr_b16 v[100:101], v3 offset:9248
	ds_read_b64_tr_b16 v[102:103], v3 offset:11552
	ds_read_b64_tr_b16 v[104:105], v3 offset:9280
	ds_read_b64_tr_b16 v[106:107], v3 offset:11584
	s_waitcnt lgkmcnt(4)
	v_mfma_f32_16x16x32_bf16 v[68:71], v[76:79], v[88:91], v[68:71]
	ds_read_b64_tr_b16 v[76:77], v3 offset:9312
	ds_read_b64_tr_b16 v[78:79], v3 offset:11616
	v_cvt_pk_bf16_f32 v50, v49, v50
	v_cvt_pk_bf16_f32 v52, v52, v55
	s_waitcnt lgkmcnt(0)
	v_mfma_f32_16x16x32_bf16 v[64:67], v[76:79], v[88:91], v[72:75]
	s_nop 2
	ds_read_b64_tr_b16 v[72:73], v3 offset:18432
	ds_read_b64_tr_b16 v[74:75], v3 offset:20736
	v_cvt_pk_bf16_f32 v76, v92, v93
	v_cvt_pk_bf16_f32 v77, v95, v97
	v_cvt_pk_bf16_f32 v78, v94, v96
	v_cvt_pk_bf16_f32 v79, v60, v98
	v_mfma_f32_16x16x32_bf16 v[80:83], v[100:103], v[88:91], v[80:83]
	v_exp_f32_e32 v60, v63
	v_add_f32_e32 v63, v61, v99
	v_sub_f32_e32 v48, v48, v2
	v_mfma_f32_16x16x32_bf16 v[84:87], v[104:107], v[88:91], v[84:87]
	ds_read_b64_tr_b16 v[88:89], v3 offset:18464
	ds_read_b64_tr_b16 v[90:91], v3 offset:20768
	ds_read_b64_tr_b16 v[92:93], v3 offset:18496
	ds_read_b64_tr_b16 v[94:95], v3 offset:20800
	v_add_f32_e32 v63, v62, v63
	s_waitcnt lgkmcnt(4)
	v_mfma_f32_16x16x32_bf16 v[68:71], v[72:75], v[76:79], v[68:71]
	ds_read_b64_tr_b16 v[72:73], v3 offset:18528
	ds_read_b64_tr_b16 v[74:75], v3 offset:20832
	v_add_f32_e32 v63, v60, v63
	v_sub_f32_e32 v9, v9, v2
	s_waitcnt lgkmcnt(0)
	v_mfma_f32_16x16x32_bf16 v[64:67], v[72:75], v[76:79], v[64:67]
	ds_read_b64_tr_b16 v[72:73], v3 offset:27648
	ds_read_b64_tr_b16 v[74:75], v3 offset:29952
	v_sub_f32_e32 v8, v8, v2
	v_cvt_pk_bf16_f32 v10, v10, v34
	v_mfma_f32_16x16x32_bf16 v[80:83], v[88:91], v[76:79], v[80:83]
	v_exp_f32_e32 v88, v54
	v_sub_f32_e32 v89, v51, v2
	v_cvt_pk_bf16_f32 v51, v53, v57
	v_cvt_pk_bf16_f32 v53, v56, v58
	v_mfma_f32_16x16x32_bf16 v[84:87], v[92:95], v[76:79], v[84:87]
	ds_read_b64_tr_b16 v[76:77], v3 offset:27680
	ds_read_b64_tr_b16 v[78:79], v3 offset:29984
	ds_read_b64_tr_b16 v[54:55], v3 offset:27712
	ds_read_b64_tr_b16 v[56:57], v3 offset:30016
	v_exp_f32_e32 v58, v89
	s_waitcnt lgkmcnt(4)
	v_mfma_f32_16x16x32_bf16 v[68:71], v[72:75], v[50:53], v[68:71]
	ds_read_b64_tr_b16 v[72:73], v3 offset:27744
	ds_read_b64_tr_b16 v[74:75], v3 offset:30048
	v_exp_f32_e32 v89, v48
	v_add_f32_e32 v48, v88, v63
	v_add_f32_e32 v48, v58, v48
	s_waitcnt lgkmcnt(4)
	v_mfma_f32_16x16x32_bf16 v[76:79], v[76:79], v[50:53], v[80:83]
	v_add_f32_e32 v63, v89, v48
	v_sub_f32_e32 v5, v5, v2
	v_sub_f32_e32 v4, v4, v2
	s_waitcnt lgkmcnt(2)
	v_mfma_f32_16x16x32_bf16 v[54:57], v[54:57], v[50:53], v[84:87]
	v_sub_f32_e32 v1, v1, v2
	v_exp_f32_e32 v1, v1
	v_sub_f32_e32 v0, v0, v2
	s_waitcnt lgkmcnt(0)
	v_mfma_f32_16x16x32_bf16 v[48:51], v[72:75], v[50:53], v[64:67]
	s_nop 2
	ds_read_b64_tr_b16 v[64:65], v3 offset:36864
	ds_read_b64_tr_b16 v[66:67], v3 offset:39168
	v_cvt_pk_bf16_f32 v72, v39, v40
	v_cvt_pk_bf16_f32 v73, v42, v45
	ds_read_b64_tr_b16 v[80:81], v3 offset:36896
	ds_read_b64_tr_b16 v[82:83], v3 offset:39200
	v_cvt_pk_bf16_f32 v74, v41, v43
	ds_read_b64_tr_b16 v[40:41], v3 offset:36928
	ds_read_b64_tr_b16 v[42:43], v3 offset:39232
	v_cvt_pk_bf16_f32 v75, v44, v46
	v_exp_f32_e32 v84, v9
	v_cvt_pk_bf16_f32 v9, v36, v38
	s_waitcnt lgkmcnt(4)
	v_mfma_f32_16x16x32_bf16 v[64:67], v[64:67], v[72:75], v[68:71]
	s_nop 2
	ds_read_b64_tr_b16 v[68:69], v3 offset:36960
	ds_read_b64_tr_b16 v[70:71], v3 offset:39264
	v_add_f32_e32 v39, v84, v63
	v_exp_f32_e32 v63, v8
	s_waitcnt lgkmcnt(2)
	v_mfma_f32_16x16x32_bf16 v[40:43], v[40:43], v[72:75], v[54:57]
	ds_read_b64_tr_b16 v[52:53], v3 offset:46080
	s_nop 1
	ds_read_b64_tr_b16 v[54:55], v3 offset:48384
	v_cvt_pk_bf16_f32 v8, v7, v11
	v_cvt_pk_bf16_f32 v11, v35, v37
	s_waitcnt lgkmcnt(2)
	v_mfma_f32_16x16x32_bf16 v[48:51], v[68:71], v[72:75], v[48:51]
	ds_read_b64_tr_b16 v[68:69], v3 offset:46112
	ds_read_b64_tr_b16 v[70:71], v3 offset:48416
	ds_read_b64_tr_b16 v[34:35], v3 offset:46144
	ds_read_b64_tr_b16 v[36:37], v3 offset:48448
	v_exp_f32_e32 v56, v5
	s_waitcnt lgkmcnt(4)
	v_mfma_f32_16x16x32_bf16 v[52:55], v[52:55], v[8:11], v[64:67]
	s_nop 2
	ds_read_b64_tr_b16 v[64:65], v3 offset:46176
	ds_read_b64_tr_b16 v[66:67], v3 offset:48480
	v_exp_f32_e32 v57, v4
	v_add_f32_e32 v4, v63, v39
	v_mfma_f32_16x16x32_bf16 v[76:79], v[80:83], v[72:75], v[76:79]
	v_cvt_pk_bf16_f32 v5, v47, v59
	v_add_f32_e32 v4, v56, v4
	v_add_f32_e32 v72, v57, v4
	s_waitcnt lgkmcnt(2)
	v_mfma_f32_16x16x32_bf16 v[34:37], v[34:37], v[8:11], v[40:43]
	ds_read_b64_tr_b16 v[38:39], v3 offset:55296
	s_nop 1
	ds_read_b64_tr_b16 v[40:41], v3 offset:57600
	ds_read_b64_tr_b16 v[42:43], v3 offset:55328
	ds_read_b64_tr_b16 v[44:45], v3 offset:57632
	v_cvt_pk_bf16_f32 v4, v6, v17
	v_mfma_f32_16x16x32_bf16 v[68:71], v[68:71], v[8:11], v[76:79]
	v_cvt_pk_bf16_f32 v6, v61, v62
	v_cvt_pk_bf16_f32 v7, v60, v88
	v_exp_f32_e32 v0, v0
	s_waitcnt lgkmcnt(4)
; __device__ __forceinline__ void natten_unit(LAS char* L, const bf16_t* Pseq  , bf16_t* Oseq  , int h, int r0, const float* rpb) {
;     ...
;         const int item = wid + 8 * it, r = r0 + (item >> 2), n = item & 3;
;         int rs = r - 4; rs = rs < 0 ? 0 : (rs > 24 ? 24 : rs);
;         int cb = 16 * n - 8; cb = cb < 0 ? 0 : (cb > 32 ? 32 : cb);
;         const int qcol = 16 * n + m; int cs = qcol - 8; cs = cs < 0 ? 0 : (cs > 48 ? 48 : cs);
;         const bf16_t* qrow = Pseq + (size_t)(r * 64 + qcol) * PPITCH + PB + h * 64 + quad * 8;
;         const bf16x8 qf0 = *(const bf16x8*)qrow, qf1 = *(const bf16x8*)(qrow + 32);
;         f32x4 sc[16];
; #pragma unroll
;         for (int t = 0; t < 16; ++t) { const int kr = t >> 1, kc0 = (t & 1) * 16;
;             const bf16_t* krow = Pseq + (size_t)((rs + kr) * 64 + cb + kc0 + m) * PPITCH + PB + 256 + h * 64 + quad * 8;
;             const bf16x8 k0 = *(const bf16x8*)krow, k1 = *(const bf16x8*)(krow + 32);
;             f32x4 a = {0.f, 0.f, 0.f, 0.f}; a = MFMA16(k0, qf0, a); a = MFMA16(k1, qf1, a);
;             const int dr = rs + kr - r + 7;
; #pragma unroll
;     ...
;         sum += __shfl_xor(sum, 16); sum += __shfl_xor(sum, 32);
;         const float inv = 1.0f / sum;
;         f32x4 o[4];
; #pragma unroll
;         for (int dt = 0; dt < 4; ++dt) o[dt] = (f32x4){0.f, 0.f, 0.f, 0.f};
;         LAS const char* Vb = L + (size_t)((rs - rs_lo) * 64 + cb + 4 * quad + (m >> 2)) * VPB + (lane & 3) * 8;
; #pragma unroll
;         for (int u = 0; u < 8; ++u) { u32x4 w; w.x = cvt_pk_bf16(sc[2 * u][0], sc[2 * u][1]); w.y = cvt_pk_bf16(sc[2 * u][2], sc[2 * u][3]);
;             w.z = cvt_pk_bf16(sc[2 * u + 1][0], sc[2 * u + 1][1]); w.w = cvt_pk_bf16(sc[2 * u + 1][2], sc[2 * u + 1][3]);
;             const bf16x8 pf = __builtin_bit_cast(bf16x8, w);
; #pragma unroll
;             for (int dt = 0; dt < 4; ++dt) { const v4i16_t lo = vtr(Vb + (u * 64) * VPB + dt * 32), hh = vtr(Vb + (u * 64 + 16) * VPB + dt * 32);
;                 const bf16x8 vf = {lo[0], lo[1], lo[2], lo[3], hh[0], hh[1], hh[2], hh[3]};
;                 o[dt] = MFMA16(vf, pf, o[dt]); } }
;         bf16_t* orow = Oseq + (size_t)(r * 64 + qcol) * 256 + h * 64 + 4 * quad;
; #pragma unroll
;         for (int dt = 0; dt < 4; ++dt) { u32x2 w; w.x = cvt_pk_bf16(o[dt][0] * inv, o[dt][1] * inv); w.y = cvt_pk_bf16(o[dt][2] * inv, o[dt][3] * inv); *(u32x2*)(orow + dt * 16) = w; }
	v_mfma_f32_16x16x32_bf16 v[8:11], v[64:67], v[8:11], v[48:51]
	ds_read_b64_tr_b16 v[46:47], v3 offset:55360
	s_nop 1
	ds_read_b64_tr_b16 v[48:49], v3 offset:57664
	v_add_f32_e32 v2, v1, v72
	v_add_f32_e32 v2, v0, v2
	s_waitcnt lgkmcnt(4)
	v_mfma_f32_16x16x32_bf16 v[38:41], v[38:41], v[4:7], v[52:55]
	ds_read_b64_tr_b16 v[50:51], v3 offset:55392
	s_nop 1
	ds_read_b64_tr_b16 v[52:53], v3 offset:57696
	ds_bpermute_b32 v17, v18, v2
	s_waitcnt lgkmcnt(0)
	v_add_f32_e32 v17, v2, v17
	v_mfma_f32_16x16x32_bf16 v[34:37], v[46:49], v[4:7], v[34:37]
	v_add_u32_e32 v48, 0x10500, v3
	ds_read_b64_tr_b16 v[46:47], v3 offset:64512
	ds_read_b64_tr_b16 v[48:49], v48
	ds_bpermute_b32 v54, v184, v17
	v_mfma_f32_16x16x32_bf16 v[42:45], v[42:45], v[4:7], v[68:71]
	v_add_u32_e32 v2, 0x10560, v3
	v_mfma_f32_16x16x32_bf16 v[4:7], v[50:53], v[4:7], v[8:11]
	ds_read_b64_tr_b16 v[50:51], v3 offset:64544
	s_nop 1
	v_add_u32_e32 v10, 0x10520, v3
	v_cvt_pk_bf16_f32 v8, v58, v89
	v_cvt_pk_bf16_f32 v9, v84, v63
	ds_read_b64_tr_b16 v[52:53], v10
	v_cvt_pk_bf16_f32 v10, v56, v57
	v_cvt_pk_bf16_f32 v11, v1, v0
	v_add_u32_e32 v0, 0x10540, v3
	s_waitcnt lgkmcnt(3)
	v_mfma_f32_16x16x32_bf16 v[38:41], v[46:49], v[8:11], v[38:41]
	ds_read_b64_tr_b16 v[46:47], v3 offset:64576
	ds_read_b64_tr_b16 v[48:49], v0
	ds_read_b64_tr_b16 v[0:1], v3 offset:64608
	ds_read_b64_tr_b16 v[2:3], v2
	s_waitcnt lgkmcnt(4)
	v_mfma_f32_16x16x32_bf16 v[42:45], v[50:53], v[8:11], v[42:45]
	v_add_f32_e32 v50, v17, v54
	v_ashrrev_i32_e32 v17, 31, v16
	s_waitcnt lgkmcnt(2)
	v_mfma_f32_16x16x32_bf16 v[34:37], v[46:49], v[8:11], v[34:37]
	v_div_scale_f32 v46, s[8:9], v50, v50, 1.0
	v_rcp_f32_e32 v47, v46
	s_waitcnt lgkmcnt(0)
	v_mfma_f32_16x16x32_bf16 v[0:3], v[0:3], v[8:11], v[4:7]
	s_mov_b32 s8, 8
	s_nop 1
	v_fma_f32 v4, -v46, v47, 1.0
	v_fmac_f32_e32 v47, v4, v47
	v_div_scale_f32 v4, vcc, 1.0, v50, 1.0
	v_mul_f32_e32 v5, v4, v47
	v_fma_f32 v6, -v46, v5, v4
	v_fmac_f32_e32 v5, v6, v47
	v_fma_f32 v4, -v46, v5, v4
	v_div_fmas_f32 v4, v4, v47, v5
	v_div_fixup_f32 v4, v4, v50, 1.0
	v_lshlrev_b64 v[6:7], 9, v[16:17]
	v_pk_mul_f32 v[8:9], v[4:5], v[38:39] op_sel_hi:[0,1]
	v_pk_mul_f32 v[10:11], v[4:5], v[40:41] op_sel_hi:[0,1]
	v_lshl_add_u64 v[6:7], v[12:13], 0, v[6:7]
	v_cvt_pk_bf16_f32 v8, v8, v9
	v_cvt_pk_bf16_f32 v9, v10, v11
	global_store_dwordx2 v[6:7], v[8:9], off
	v_pk_mul_f32 v[8:9], v[4:5], v[42:43] op_sel_hi:[0,1]
	v_pk_mul_f32 v[10:11], v[4:5], v[44:45] op_sel_hi:[0,1]
	v_cvt_pk_bf16_f32 v8, v8, v9
	v_cvt_pk_bf16_f32 v9, v10, v11
	global_store_dwordx2 v[6:7], v[8:9], off offset:32
	v_pk_mul_f32 v[8:9], v[4:5], v[34:35] op_sel_hi:[0,1]
	v_pk_mul_f32 v[10:11], v[4:5], v[36:37] op_sel_hi:[0,1]
	v_pk_mul_f32 v[0:1], v[4:5], v[0:1] op_sel_hi:[0,1]
	v_pk_mul_f32 v[2:3], v[4:5], v[2:3] op_sel_hi:[0,1]
	v_cvt_pk_bf16_f32 v8, v8, v9
	v_cvt_pk_bf16_f32 v9, v10, v11
	v_cvt_pk_bf16_f32 v0, v0, v1
	v_cvt_pk_bf16_f32 v1, v2, v3
	s_andn2_b64 vcc, exec, s[38:39]
	s_mov_b64 s[38:39], 0
	global_store_dwordx2 v[6:7], v[8:9], off offset:64
	global_store_dwordx2 v[6:7], v[0:1], off offset:96
	s_cbranch_vccz .LBB0_650
.LBB0_677:
	v_add_u32_e32 v0, s8, v20
	v_ashrrev_i32_e32 v0, 2, v0
	v_add_u32_e32 v206, s33, v0
	v_med3_i32 v207, v206, 4, 28
	v_add_u32_e32 v17, -4, v207
	v_lshl_or_b32 v16, v206, 6, v21
	v_mad_i64_i32 v[0:1], s[8:9], v16, s56, v[14:15]
	global_load_dwordx4 v[4:7], v[0:1], off offset:1536
	s_nop 0
	global_load_dwordx4 v[0:3], v[0:1], off offset:1600
	v_lshlrev_b32_e32 v210, 6, v17
	v_add_u32_e32 v210, v210, v22
	v_mov_b32_e32 v211, v210
	v_mad_u64_u32 v[204:205], s[8:9], v211, s56, v[14:15]
	global_load_dwordx4 v[116:119], v[204:205], off offset:2048
	global_load_dwordx4 v[120:123], v[204:205], off offset:2112
	v_add_u32_e32 v211, 0x10, v210
	v_mad_u64_u32 v[204:205], s[8:9], v211, s56, v[14:15]
	global_load_dwordx4 v[124:127], v[204:205], off offset:2048
	global_load_dwordx4 v[128:131], v[204:205], off offset:2112
	v_add_u32_e32 v211, 0x40, v210
	v_mad_u64_u32 v[204:205], s[8:9], v211, s56, v[14:15]
	global_load_dwordx4 v[132:135], v[204:205], off offset:2048
	global_load_dwordx4 v[136:139], v[204:205], off offset:2112
	v_add_u32_e32 v211, 0x50, v210
	v_mad_u64_u32 v[204:205], s[8:9], v211, s56, v[14:15]
	global_load_dwordx4 v[140:143], v[204:205], off offset:2048
	global_load_dwordx4 v[144:147], v[204:205], off offset:2112
	v_add_u32_e32 v211, 0x80, v210
	v_mad_u64_u32 v[204:205], s[8:9], v211, s56, v[14:15]
	global_load_dwordx4 v[148:151], v[204:205], off offset:2048
	global_load_dwordx4 v[152:155], v[204:205], off offset:2112
	v_add_u32_e32 v211, 0x90, v210
	v_mad_u64_u32 v[204:205], s[8:9], v211, s56, v[14:15]
	global_load_dwordx4 v[164:167], v[204:205], off offset:2048
	global_load_dwordx4 v[168:171], v[204:205], off offset:2112
	v_add_u32_e32 v211, 0xc0, v210
	v_mad_u64_u32 v[204:205], s[8:9], v211, s56, v[14:15]
	global_load_dwordx4 v[172:175], v[204:205], off offset:2048
	global_load_dwordx4 v[176:179], v[204:205], off offset:2112
	v_add_u32_e32 v211, 0xd0, v210
	v_mad_u64_u32 v[204:205], s[8:9], v211, s56, v[14:15]
	global_load_dwordx4 v[196:199], v[204:205], off offset:2048
	global_load_dwordx4 v[200:203], v[204:205], off offset:2112
	s_add_i32 s16, 0, 0x18c00
	v_sub_u32_e32 v208, v17, v206
	v_mul_lo_u32 v208, v208, s64
	v_add_u32_e32 v208, s16, v208
	v_mov_b32_e32 v189, 0xff800000
	v_lshl_add_u32 v180, v25, 2, v208
	v_lshl_add_u32 v181, v26, 2, v208
	v_lshl_add_u32 v182, v27, 2, v208
	v_lshl_add_u32 v183, v28, 2, v208
	v_lshl_add_u32 v185, v30, 2, v208
	v_lshl_add_u32 v186, v31, 2, v208
	v_lshl_add_u32 v187, v32, 2, v208
	v_lshl_add_u32 v188, v33, 2, v208
	s_waitcnt lgkmcnt(0)
	s_waitcnt vmcnt(14)
; #define MFMA16(a, b, c) __builtin_amdgcn_mfma_f32_16x16x32_bf16((a), (b), (c), 0, 0, 0)
; __device__ __forceinline__ void natten_unit(LAS char* L, const bf16_t* Pseq  , bf16_t* Oseq  , int h, int r0, const float* rpb) {
;     ...
; #pragma unroll
;         for (int t = 0; t < 16; ++t) { const int kr = t >> 1, kc0 = (t & 1) * 16;
;             const bf16_t* krow = Pseq + (size_t)((rs + kr) * 64 + cb + kc0 + m) * PPITCH + PB + 256 + h * 64 + quad * 8;
;             const bf16x8 k0 = *(const bf16x8*)krow, k1 = *(const bf16x8*)(krow + 32);
;             f32x4 a = {0.f, 0.f, 0.f, 0.f}; a = MFMA16(k0, qf0, a); a = MFMA16(k1, qf1, a);
;             const int dr = rs + kr - r + 7;
; #pragma unroll
;             for (int j = 0; j < 4; ++j) { const int kcol = cb + kc0 + 4 * quad + j; const bool ok = (kcol >= cs) && (kcol < cs + 16); int dc = kcol - qcol + 15; dc = dc < 0 ? 0 : (dc > 30 ? 30 : dc);
;                 a[j] = ok ? a[j] + rpbL[dr * 31 + dc] : -INFINITY; }
;             sc[t] = a; }
	v_mfma_f32_16x16x32_bf16 v[212:215], v[116:119], v[4:7], 0
	v_mfma_f32_16x16x32_bf16 v[212:215], v[120:123], v[0:3], v[212:215]
	v_add_u32_e32 v211, 0x100, v210
	v_mad_u64_u32 v[204:205], s[8:9], v211, s56, v[14:15]
	global_load_dwordx4 v[116:119], v[204:205], off offset:2048
	global_load_dwordx4 v[120:123], v[204:205], off offset:2112
	ds_read_b32 v220, v180 offset:928
	ds_read_b32 v221, v181 offset:928
	ds_read_b32 v222, v182 offset:928
	ds_read_b32 v223, v183 offset:928
	s_waitcnt vmcnt(14)
	v_mfma_f32_16x16x32_bf16 v[216:219], v[124:127], v[4:7], 0
	v_mfma_f32_16x16x32_bf16 v[216:219], v[128:131], v[0:3], v[216:219]
	v_add_u32_e32 v211, 0x110, v210
	v_mad_u64_u32 v[204:205], s[8:9], v211, s56, v[14:15]
	global_load_dwordx4 v[124:127], v[204:205], off offset:2048
	global_load_dwordx4 v[128:131], v[204:205], off offset:2112
	ds_read_b32 v224, v185 offset:928
	ds_read_b32 v225, v186 offset:928
	ds_read_b32 v226, v187 offset:928
	ds_read_b32 v227, v188 offset:928
	s_waitcnt lgkmcnt(4)
	s_nop 1
	v_add_f32_e32 v209, v212, v220
	v_cndmask_b32_e64 v35, v189, v209, s[10:11]
	v_add_f32_e32 v209, v213, v221
	v_cndmask_b32_e64 v34, v189, v209, s[12:13]
	v_add_f32_e32 v209, v214, v222
	v_cndmask_b32_e64 v37, v189, v209, s[14:15]
	v_add_f32_e32 v209, v215, v223
	v_cndmask_b32_e64 v36, v189, v209, s[20:21]
	s_waitcnt vmcnt(14)
	v_mfma_f32_16x16x32_bf16 v[212:215], v[132:135], v[4:7], 0
	v_mfma_f32_16x16x32_bf16 v[212:215], v[136:139], v[0:3], v[212:215]
	v_add_u32_e32 v211, 0x140, v210
	v_mad_u64_u32 v[204:205], s[8:9], v211, s56, v[14:15]
	global_load_dwordx4 v[132:135], v[204:205], off offset:2048
	global_load_dwordx4 v[136:139], v[204:205], off offset:2112
	ds_read_b32 v220, v180 offset:1052
	ds_read_b32 v221, v181 offset:1052
	ds_read_b32 v222, v182 offset:1052
	ds_read_b32 v223, v183 offset:1052
	s_waitcnt lgkmcnt(4)
	s_nop 1
	v_add_f32_e32 v209, v216, v224
	v_cndmask_b32_e64 v39, v189, v209, s[22:23]
	v_add_f32_e32 v209, v217, v225
	v_cndmask_b32_e64 v38, v189, v209, s[28:29]
	v_add_f32_e32 v209, v218, v226
	v_cndmask_b32_e64 v41, v189, v209, s[34:35]
	v_add_f32_e32 v209, v219, v227
	v_cndmask_b32_e64 v40, v189, v209, s[36:37]
	s_waitcnt vmcnt(14)
	v_mfma_f32_16x16x32_bf16 v[216:219], v[140:143], v[4:7], 0
	v_mfma_f32_16x16x32_bf16 v[216:219], v[144:147], v[0:3], v[216:219]
	v_add_u32_e32 v211, 0x150, v210
	v_mad_u64_u32 v[204:205], s[8:9], v211, s56, v[14:15]
	global_load_dwordx4 v[140:143], v[204:205], off offset:2048
	global_load_dwordx4 v[144:147], v[204:205], off offset:2112
	ds_read_b32 v224, v185 offset:1052
	ds_read_b32 v225, v186 offset:1052
	ds_read_b32 v226, v187 offset:1052
	ds_read_b32 v227, v188 offset:1052
	s_waitcnt lgkmcnt(4)
	s_nop 1
	v_add_f32_e32 v209, v212, v220
	v_cndmask_b32_e64 v43, v189, v209, s[10:11]
	v_add_f32_e32 v209, v213, v221
	v_cndmask_b32_e64 v42, v189, v209, s[12:13]
	v_add_f32_e32 v209, v214, v222
	v_cndmask_b32_e64 v45, v189, v209, s[14:15]
	v_add_f32_e32 v209, v215, v223
	v_cndmask_b32_e64 v44, v189, v209, s[20:21]
	s_waitcnt vmcnt(14)
	v_mfma_f32_16x16x32_bf16 v[212:215], v[148:151], v[4:7], 0
	v_mfma_f32_16x16x32_bf16 v[212:215], v[152:155], v[0:3], v[212:215]
	v_add_u32_e32 v211, 0x180, v210
	v_mad_u64_u32 v[204:205], s[8:9], v211, s56, v[14:15]
	global_load_dwordx4 v[148:151], v[204:205], off offset:2048
	global_load_dwordx4 v[152:155], v[204:205], off offset:2112
	ds_read_b32 v220, v180 offset:1176
	ds_read_b32 v221, v181 offset:1176
	ds_read_b32 v222, v182 offset:1176
	ds_read_b32 v223, v183 offset:1176
	s_waitcnt lgkmcnt(4)
	s_nop 1
	v_add_f32_e32 v209, v216, v224
	v_cndmask_b32_e64 v47, v189, v209, s[22:23]
	v_add_f32_e32 v209, v217, v225
	v_cndmask_b32_e64 v46, v189, v209, s[28:29]
	v_add_f32_e32 v209, v218, v226
	v_cndmask_b32_e64 v50, v189, v209, s[34:35]
	v_add_f32_e32 v209, v219, v227
	v_cndmask_b32_e64 v49, v189, v209, s[36:37]
	s_waitcnt vmcnt(14)
	v_mfma_f32_16x16x32_bf16 v[216:219], v[164:167], v[4:7], 0
	v_mfma_f32_16x16x32_bf16 v[216:219], v[168:171], v[0:3], v[216:219]
	v_add_u32_e32 v211, 0x190, v210
	v_mad_u64_u32 v[204:205], s[8:9], v211, s56, v[14:15]
	global_load_dwordx4 v[164:167], v[204:205], off offset:2048
	global_load_dwordx4 v[168:171], v[204:205], off offset:2112
	ds_read_b32 v224, v185 offset:1176
	ds_read_b32 v225, v186 offset:1176
	ds_read_b32 v226, v187 offset:1176
	ds_read_b32 v227, v188 offset:1176
	s_waitcnt lgkmcnt(4)
	s_nop 1
	v_add_f32_e32 v209, v212, v220
	v_cndmask_b32_e64 v53, v189, v209, s[10:11]
	v_add_f32_e32 v209, v213, v221
	v_cndmask_b32_e64 v52, v189, v209, s[12:13]
	v_add_f32_e32 v209, v214, v222
	v_cndmask_b32_e64 v56, v189, v209, s[14:15]
	v_add_f32_e32 v209, v215, v223
	v_cndmask_b32_e64 v55, v189, v209, s[20:21]
	s_waitcnt vmcnt(14)
	v_mfma_f32_16x16x32_bf16 v[212:215], v[172:175], v[4:7], 0
	v_mfma_f32_16x16x32_bf16 v[212:215], v[176:179], v[0:3], v[212:215]
	v_add_u32_e32 v211, 0x1c0, v210
	v_mad_u64_u32 v[204:205], s[8:9], v211, s56, v[14:15]
	global_load_dwordx4 v[172:175], v[204:205], off offset:2048
	global_load_dwordx4 v[176:179], v[204:205], off offset:2112
	ds_read_b32 v220, v180 offset:1300
	ds_read_b32 v221, v181 offset:1300
	ds_read_b32 v222, v182 offset:1300
	ds_read_b32 v223, v183 offset:1300
	s_waitcnt lgkmcnt(4)
	s_nop 1
	v_add_f32_e32 v209, v216, v224
	v_cndmask_b32_e64 v58, v189, v209, s[22:23]
	v_add_f32_e32 v209, v217, v225
	v_cndmask_b32_e64 v57, v189, v209, s[28:29]
	v_add_f32_e32 v209, v218, v226
	v_cndmask_b32_e64 v60, v189, v209, s[34:35]
	v_add_f32_e32 v209, v219, v227
	v_cndmask_b32_e64 v59, v189, v209, s[36:37]
	s_waitcnt vmcnt(14)
; #define MFMA16(a, b, c) __builtin_amdgcn_mfma_f32_16x16x32_bf16((a), (b), (c), 0, 0, 0)
; __device__ __forceinline__ void natten_unit(LAS char* L, const bf16_t* Pseq  , bf16_t* Oseq  , int h, int r0, const float* rpb) {
;     ...
; #pragma unroll
;         for (int t = 0; t < 16; ++t) { const int kr = t >> 1, kc0 = (t & 1) * 16;
;             const bf16_t* krow = Pseq + (size_t)((rs + kr) * 64 + cb + kc0 + m) * PPITCH + PB + 256 + h * 64 + quad * 8;
;             const bf16x8 k0 = *(const bf16x8*)krow, k1 = *(const bf16x8*)(krow + 32);
;             f32x4 a = {0.f, 0.f, 0.f, 0.f}; a = MFMA16(k0, qf0, a); a = MFMA16(k1, qf1, a);
;             const int dr = rs + kr - r + 7;
; #pragma unroll
;             for (int j = 0; j < 4; ++j) { const int kcol = cb + kc0 + 4 * quad + j; const bool ok = (kcol >= cs) && (kcol < cs + 16); int dc = kcol - qcol + 15; dc = dc < 0 ? 0 : (dc > 30 ? 30 : dc);
;                 a[j] = ok ? a[j] + rpbL[dr * 31 + dc] : -INFINITY; }
;             sc[t] = a; }
	v_mfma_f32_16x16x32_bf16 v[216:219], v[196:199], v[4:7], 0
	v_mfma_f32_16x16x32_bf16 v[216:219], v[200:203], v[0:3], v[216:219]
	v_add_u32_e32 v211, 0x1d0, v210
	v_mad_u64_u32 v[204:205], s[8:9], v211, s56, v[14:15]
	global_load_dwordx4 v[196:199], v[204:205], off offset:2048
	global_load_dwordx4 v[200:203], v[204:205], off offset:2112
	ds_read_b32 v224, v185 offset:1300
	ds_read_b32 v225, v186 offset:1300
	ds_read_b32 v226, v187 offset:1300
	ds_read_b32 v227, v188 offset:1300
	s_waitcnt lgkmcnt(4)
	s_nop 1
	v_add_f32_e32 v209, v212, v220
	v_cndmask_b32_e64 v62, v189, v209, s[10:11]
	v_add_f32_e32 v209, v213, v221
	v_cndmask_b32_e64 v61, v189, v209, s[12:13]
	v_add_f32_e32 v209, v214, v222
	v_cndmask_b32_e64 v66, v189, v209, s[14:15]
	v_add_f32_e32 v209, v215, v223
	v_cndmask_b32_e64 v64, v189, v209, s[20:21]
	s_waitcnt vmcnt(14)
	v_mfma_f32_16x16x32_bf16 v[212:215], v[116:119], v[4:7], 0
	v_mfma_f32_16x16x32_bf16 v[212:215], v[120:123], v[0:3], v[212:215]
	ds_read_b32 v220, v180 offset:1424
	ds_read_b32 v221, v181 offset:1424
	ds_read_b32 v222, v182 offset:1424
	ds_read_b32 v223, v183 offset:1424
	s_waitcnt lgkmcnt(4)
	s_nop 1
	v_add_f32_e32 v209, v216, v224
	v_cndmask_b32_e64 v69, v189, v209, s[22:23]
	v_add_f32_e32 v209, v217, v225
	v_cndmask_b32_e64 v68, v189, v209, s[28:29]
	v_add_f32_e32 v209, v218, v226
	v_cndmask_b32_e64 v71, v189, v209, s[34:35]
	v_add_f32_e32 v209, v219, v227
	v_cndmask_b32_e64 v70, v189, v209, s[36:37]
	s_waitcnt vmcnt(12)
	v_mfma_f32_16x16x32_bf16 v[216:219], v[124:127], v[4:7], 0
	v_mfma_f32_16x16x32_bf16 v[216:219], v[128:131], v[0:3], v[216:219]
	ds_read_b32 v224, v185 offset:1424
	ds_read_b32 v225, v186 offset:1424
	ds_read_b32 v226, v187 offset:1424
	ds_read_b32 v227, v188 offset:1424
	s_waitcnt lgkmcnt(4)
	s_nop 1
	v_add_f32_e32 v209, v212, v220
	v_cndmask_b32_e64 v74, v189, v209, s[10:11]
	v_add_f32_e32 v209, v213, v221
	v_cndmask_b32_e64 v73, v189, v209, s[12:13]
	v_add_f32_e32 v209, v214, v222
	v_cndmask_b32_e64 v77, v189, v209, s[14:15]
	v_add_f32_e32 v209, v215, v223
	v_cndmask_b32_e64 v76, v189, v209, s[20:21]
	s_waitcnt vmcnt(10)
	v_mfma_f32_16x16x32_bf16 v[212:215], v[132:135], v[4:7], 0
	v_mfma_f32_16x16x32_bf16 v[212:215], v[136:139], v[0:3], v[212:215]
	ds_read_b32 v220, v180 offset:1548
	ds_read_b32 v221, v181 offset:1548
	ds_read_b32 v222, v182 offset:1548
	ds_read_b32 v223, v183 offset:1548
	s_waitcnt lgkmcnt(4)
	s_nop 1
	v_add_f32_e32 v209, v216, v224
	v_cndmask_b32_e64 v79, v189, v209, s[22:23]
	v_add_f32_e32 v209, v217, v225
	v_cndmask_b32_e64 v78, v189, v209, s[28:29]
	v_add_f32_e32 v209, v218, v226
	v_cndmask_b32_e64 v81, v189, v209, s[34:35]
	v_add_f32_e32 v209, v219, v227
	v_cndmask_b32_e64 v80, v189, v209, s[36:37]
	s_waitcnt vmcnt(8)
	v_mfma_f32_16x16x32_bf16 v[216:219], v[140:143], v[4:7], 0
	v_mfma_f32_16x16x32_bf16 v[216:219], v[144:147], v[0:3], v[216:219]
	ds_read_b32 v224, v185 offset:1548
	ds_read_b32 v225, v186 offset:1548
	ds_read_b32 v226, v187 offset:1548
	ds_read_b32 v227, v188 offset:1548
	s_waitcnt lgkmcnt(4)
	s_nop 1
	v_add_f32_e32 v209, v212, v220
	v_cndmask_b32_e64 v83, v189, v209, s[10:11]
	v_add_f32_e32 v209, v213, v221
	v_cndmask_b32_e64 v82, v189, v209, s[12:13]
	v_add_f32_e32 v209, v214, v222
	v_cndmask_b32_e64 v85, v189, v209, s[14:15]
	v_add_f32_e32 v209, v215, v223
	v_cndmask_b32_e64 v84, v189, v209, s[20:21]
	s_waitcnt vmcnt(6)
	v_mfma_f32_16x16x32_bf16 v[212:215], v[148:151], v[4:7], 0
	v_mfma_f32_16x16x32_bf16 v[212:215], v[152:155], v[0:3], v[212:215]
	ds_read_b32 v220, v180 offset:1672
	ds_read_b32 v221, v181 offset:1672
	ds_read_b32 v222, v182 offset:1672
	ds_read_b32 v223, v183 offset:1672
	s_waitcnt lgkmcnt(4)
	s_nop 1
	v_add_f32_e32 v209, v216, v224
	v_cndmask_b32_e64 v87, v189, v209, s[22:23]
	v_add_f32_e32 v209, v217, v225
	v_cndmask_b32_e64 v86, v189, v209, s[28:29]
	v_add_f32_e32 v209, v218, v226
	v_cndmask_b32_e64 v89, v189, v209, s[34:35]
	v_add_f32_e32 v209, v219, v227
	v_cndmask_b32_e64 v88, v189, v209, s[36:37]
	s_waitcnt vmcnt(4)
	v_mfma_f32_16x16x32_bf16 v[216:219], v[164:167], v[4:7], 0
	v_mfma_f32_16x16x32_bf16 v[216:219], v[168:171], v[0:3], v[216:219]
	ds_read_b32 v224, v185 offset:1672
	ds_read_b32 v225, v186 offset:1672
	ds_read_b32 v226, v187 offset:1672
	ds_read_b32 v227, v188 offset:1672
	s_waitcnt lgkmcnt(4)
	s_nop 1
	v_add_f32_e32 v209, v212, v220
	v_cndmask_b32_e64 v91, v189, v209, s[10:11]
	v_add_f32_e32 v209, v213, v221
	v_cndmask_b32_e64 v90, v189, v209, s[12:13]
	v_add_f32_e32 v209, v214, v222
	v_cndmask_b32_e64 v75, v189, v209, s[14:15]
	v_add_f32_e32 v209, v215, v223
	v_cndmask_b32_e64 v72, v189, v209, s[20:21]
	s_waitcnt vmcnt(2)
	v_mfma_f32_16x16x32_bf16 v[212:215], v[172:175], v[4:7], 0
	v_mfma_f32_16x16x32_bf16 v[212:215], v[176:179], v[0:3], v[212:215]
	ds_read_b32 v220, v180 offset:1796
	ds_read_b32 v221, v181 offset:1796
	ds_read_b32 v222, v182 offset:1796
	ds_read_b32 v223, v183 offset:1796
	s_waitcnt lgkmcnt(4)
	s_nop 1
	v_add_f32_e32 v209, v216, v224
	v_cndmask_b32_e64 v65, v189, v209, s[22:23]
	v_add_f32_e32 v209, v217, v225
	v_cndmask_b32_e64 v63, v189, v209, s[28:29]
	v_add_f32_e32 v209, v218, v226
	v_cndmask_b32_e64 v67, v189, v209, s[34:35]
	v_add_f32_e32 v209, v219, v227
	v_cndmask_b32_e64 v54, v189, v209, s[36:37]
	s_waitcnt vmcnt(0)
	v_mfma_f32_16x16x32_bf16 v[216:219], v[196:199], v[4:7], 0
	v_mfma_f32_16x16x32_bf16 v[216:219], v[200:203], v[0:3], v[216:219]
	ds_read_b32 v224, v185 offset:1796
	ds_read_b32 v225, v186 offset:1796
	ds_read_b32 v226, v187 offset:1796
	ds_read_b32 v227, v188 offset:1796
	s_waitcnt lgkmcnt(4)
	s_nop 1
	v_add_f32_e32 v209, v212, v220
	v_cndmask_b32_e64 v51, v189, v209, s[10:11]
	v_add_f32_e32 v209, v213, v221
	v_cndmask_b32_e64 v48, v189, v209, s[12:13]
	v_add_f32_e32 v209, v214, v222
	v_cndmask_b32_e64 v9, v189, v209, s[14:15]
	v_add_f32_e32 v209, v215, v223
	v_cndmask_b32_e64 v8, v189, v209, s[20:21]
	s_waitcnt lgkmcnt(0)
	s_nop 7
	v_add_f32_e32 v209, v216, v224
	v_cndmask_b32_e64 v5, v189, v209, s[22:23]
	v_add_f32_e32 v209, v217, v225
	v_cndmask_b32_e64 v4, v189, v209, s[28:29]
	v_add_f32_e32 v209, v218, v226
	v_cndmask_b32_e64 v1, v189, v209, s[34:35]
	v_add_f32_e32 v209, v219, v227
	v_cndmask_b32_e64 v0, v189, v209, s[36:37]
	s_mov_b64 s[8:9], exec
	s_branch .LBB0_676
